# baseline (speedup 1.0000x reference)
.LBB0_566:
	v_mov_b32_e32 v68, v190
	s_ashr_i32 s6, s0, 3
	v_bfe_u32 v0, v68, 4, 2
	v_readlane_b32 s4, v240, 36
	s_and_b32 s1, s0, 7
	v_readlane_b32 s8, v240, 22
	v_or_b32_e32 v24, s4, v0
	s_mul_i32 s4, s6, 0xc00
	s_ashr_i32 s5, s4, 31
	s_lshl_b64 s[4:5], s[4:5], 2
	v_readlane_b32 s9, v240, 23
	s_add_u32 s4, s8, s4
	s_addc_u32 s5, s9, s5
	s_lshl_b32 s7, s1, 9
	s_add_u32 s10, s4, s7
	s_addc_u32 s11, s5, 0
	s_lshl_b32 s4, s6, 10
	s_ashr_i32 s5, s4, 31
	s_ashr_i32 s7, s6, 31
	s_lshl_b64 s[4:5], s[4:5], 2
	v_readlane_b32 s8, v240, 24
	v_readlane_b32 s9, v240, 25
	s_add_u32 s8, s8, s4
	s_addc_u32 s9, s9, s5
	s_lshl_b32 s12, s0, 6
	s_and_b32 s12, s12, 0x180
	v_lshlrev_b32_e32 v0, 3, v68
	s_lshl_b32 s13, s12, 2
	v_and_b32_e32 v74, 0x78, v0
	s_add_u32 s8, s8, s13
	v_sub_u32_e32 v0, 0x7ff, v24
	s_addc_u32 s9, s9, 0
	v_ashrrev_i32_e32 v1, 31, v0
	s_lshl_b64 s[6:7], s[6:7], 20
	v_lshlrev_b64 v[0:1], 9, v[0:1]
	s_or_b32 s6, s6, s12
	v_lshl_add_u64 v[0:1], v[0:1], 0, s[6:7]
	v_readlane_b32 s40, v241, 8
	v_or_b32_e32 v0, v0, v74
	v_readlane_b32 s44, v241, 12
	v_readlane_b32 s45, v241, 13
	v_readlane_b32 s46, v241, 14
	v_readlane_b32 s47, v241, 15
	v_readlane_b32 s48, v241, 16
	v_readlane_b32 s49, v241, 17
	v_readlane_b32 s50, v241, 18
	v_readlane_b32 s51, v241, 19
	v_lshlrev_b64 v[8:9], 2, v[0:1]
	v_readlane_b32 s52, v241, 20
	v_readlane_b32 s53, v241, 21
	v_readlane_b32 s54, v241, 22
	v_readlane_b32 s55, v241, 23
	s_mov_b64 s[44:45], s[48:49]
	v_lshl_add_u64 v[10:11], s[44:45], 0, v[8:9]
	v_lshlrev_b32_e32 v128, 2, v74
	global_load_dwordx4 v[16:19], v[10:11], off
	global_load_dwordx4 v[4:7], v128, s[10:11]
	global_load_dwordx4 v[0:3], v128, s[10:11] offset:16
	global_load_dwordx4 v[20:23], v[10:11], off offset:16
	v_sub_u32_e32 v10, 0x7df, v24
	v_ashrrev_i32_e32 v11, 31, v10
	v_lshlrev_b64 v[10:11], 9, v[10:11]
	v_lshl_add_u64 v[10:11], v[10:11], 0, s[6:7]
	v_or_b32_e32 v10, v10, v74
	v_lshlrev_b64 v[42:43], 2, v[10:11]
	v_lshl_add_u64 v[10:11], s[44:45], 0, v[42:43]
	global_load_dwordx4 v[26:29], v[10:11], off
	global_load_dwordx4 v[30:33], v[10:11], off offset:16
	v_and_b32_e32 v11, 64, v214
	v_xor_b32_e32 v10, 1, v214
	v_add_u32_e32 v69, 64, v11
	v_xor_b32_e32 v12, 2, v214
	v_cmp_lt_i32_e32 vcc, v10, v69
	s_mov_b64 s[46:47], s[50:51]
	v_sub_u32_e32 v34, 0x7bf, v24
	v_cndmask_b32_e32 v45, v214, v10, vcc
	v_cmp_lt_i32_e32 vcc, v12, v69
	v_ashrrev_i32_e32 v35, 31, v34
	v_lshlrev_b64 v[34:35], 9, v[34:35]
	v_cndmask_b32_e32 v48, v214, v12, vcc
	v_lshl_add_u64 v[12:13], s[46:47], 0, v[8:9]
	global_load_dwordx4 v[8:11], v[12:13], off offset:16
	s_nop 0
	global_load_dwordx4 v[12:15], v[12:13], off
	v_lshl_add_u64 v[34:35], v[34:35], 0, s[6:7]
	v_or_b32_e32 v34, v34, v74
	v_lshlrev_b64 v[46:47], 2, v[34:35]
	v_lshl_add_u64 v[38:39], s[44:45], 0, v[46:47]
	global_load_dwordx4 v[34:37], v[38:39], off offset:16
	s_nop 0
	global_load_dwordx4 v[38:41], v[38:39], off
	v_xor_b32_e32 v25, 4, v214
	v_xor_b32_e32 v44, 8, v214
	v_cmp_lt_i32_e32 vcc, v25, v69
	v_lshlrev_b32_e32 v72, 2, v45
	v_lshlrev_b32_e32 v73, 2, v48
	v_cndmask_b32_e32 v25, v214, v25, vcc
	v_cmp_lt_i32_e32 vcc, v44, v69
	v_lshl_add_u64 v[48:49], s[46:47], 0, v[42:43]
	v_lshlrev_b32_e32 v71, 2, v25
	v_cndmask_b32_e32 v44, v214, v44, vcc
	v_lshlrev_b32_e32 v70, 2, v44
	v_sub_u32_e32 v44, 0x79f, v24
	v_ashrrev_i32_e32 v45, 31, v44
	v_lshlrev_b64 v[44:45], 9, v[44:45]
	v_lshl_add_u64 v[44:45], v[44:45], 0, s[6:7]
	v_or_b32_e32 v44, v44, v74
	v_lshlrev_b64 v[52:53], 2, v[44:45]
	v_lshl_add_u64 v[62:63], s[44:45], 0, v[52:53]
	global_load_dwordx4 v[42:45], v[48:49], off offset:16
	global_load_dwordx4 v[54:57], v[48:49], off
	global_load_dwordx4 v[58:61], v[62:63], off offset:16
	s_nop 0
	global_load_dwordx4 v[62:65], v[62:63], off
	v_lshl_add_u64 v[50:51], s[10:11], 0, v[128:129]
	v_cmp_eq_u32_e64 s[38:39], 0, v24
	v_readlane_b32 s41, v241, 9
	v_readlane_b32 s42, v241, 10
	v_readlane_b32 s43, v241, 11
	s_mov_b64 s[48:49], s[52:53]
	s_mov_b64 s[50:51], s[54:55]
	s_waitcnt vmcnt(12)
	v_pk_mul_f32 v[18:19], v[6:7], v[18:19]
	v_pk_mul_f32 v[16:17], v[4:5], v[16:17]
	s_waitcnt vmcnt(10)
	v_pk_mul_f32 v[22:23], v[2:3], v[22:23]
	v_pk_mul_f32 v[20:21], v[0:1], v[20:21]
	v_pk_mov_b32 v[48:49], v[16:17], v[18:19] op_sel:[1,0]
	v_mov_b32_e32 v17, v19
	v_mov_b32_e32 v18, v22
	v_mov_b32_e32 v19, v20
	v_mov_b32_e32 v20, v23
	v_pk_add_f32 v[16:17], v[48:49], v[16:17]
	v_pk_add_f32 v[18:19], v[18:19], v[20:21]
	v_add_f32_e32 v16, v16, v17
	v_add_f32_e32 v16, v16, v19
	v_add_f32_e32 v25, v18, v16
	s_nop 1
	v_mov_b32_dpp v48, v25 quad_perm:[1,0,3,2] row_mask:0xf bank_mask:0xf
	s_waitcnt vmcnt(9)
	v_pk_mul_f32 v[16:17], v[6:7], v[28:29]
	v_pk_mul_f32 v[18:19], v[4:5], v[26:27]
	s_waitcnt vmcnt(8)
	v_pk_mul_f32 v[20:21], v[2:3], v[32:33]
	v_pk_mul_f32 v[22:23], v[0:1], v[30:31]
	s_waitcnt lgkmcnt(0)
	v_add_f32_e32 v25, v25, v48
	s_nop 1
	v_mov_b32_dpp v28, v25 quad_perm:[2,3,0,1] row_mask:0xf bank_mask:0xf
	v_pk_mov_b32 v[26:27], v[18:19], v[16:17] op_sel:[1,0]
	v_mov_b32_e32 v19, v17
	v_mov_b32_e32 v16, v20
	v_mov_b32_e32 v17, v22
	s_waitcnt lgkmcnt(0)
	v_add_f32_e32 v20, v25, v28
	v_mov_b32_e32 v22, v21
	v_pk_add_f32 v[18:19], v[26:27], v[18:19]
	s_nop 1
	v_mov_b32_dpp v25, v20 row_half_mirror row_mask:0xf bank_mask:0xf
	s_nop 1
	v_mov_b32_dpp v25, v25 quad_perm:[3,2,1,0] row_mask:0xf bank_mask:0xf
	v_pk_add_f32 v[16:17], v[16:17], v[22:23]
	v_add_f32_e32 v18, v18, v19
	v_add_f32_e32 v17, v18, v17
	v_add_f32_e32 v18, v16, v17
	s_nop 1
	v_mov_b32_dpp v30, v18 quad_perm:[1,0,3,2] row_mask:0xf bank_mask:0xf
	s_waitcnt lgkmcnt(1)
	v_add_f32_e32 v19, v20, v25
	s_nop 1
	v_mov_b32_dpp v25, v19 row_mirror row_mask:0xf bank_mask:0xf
	s_nop 1
	v_mov_b32_dpp v25, v25 row_half_mirror row_mask:0xf bank_mask:0xf
	v_lshl_add_u64 v[16:17], s[46:47], 0, v[46:47]
	global_load_dwordx4 v[20:23], v[16:17], off offset:16
	global_load_dwordx4 v[26:29], v[16:17], off
	s_waitcnt lgkmcnt(1)
	v_add_f32_e32 v16, v18, v30
	s_nop 1
	v_mov_b32_dpp v17, v16 quad_perm:[2,3,0,1] row_mask:0xf bank_mask:0xf
	s_waitcnt lgkmcnt(1)
	v_add_f32_e32 v18, v19, v25
	v_max_f32_e32 v25, 0xf149f2ca, v18
	v_sub_f32_e32 v18, v18, v25
	v_lshl_add_u64 v[48:49], s[8:9], 0, v[128:129]
	v_exp_f32_e32 v128, v18
	s_waitcnt lgkmcnt(0)
	v_add_f32_e32 v18, v16, v17
	s_nop 1
	v_mov_b32_dpp v19, v18 row_half_mirror row_mask:0xf bank_mask:0xf
	s_nop 1
	v_mov_b32_dpp v19, v19 quad_perm:[3,2,1,0] row_mask:0xf bank_mask:0xf
	v_sub_f32_e32 v16, 0xf149f2ca, v25
	v_exp_f32_e32 v17, v16
	s_waitcnt vmcnt(9)
	v_mov_b32_e32 v16, v11
	s_waitcnt vmcnt(6)
	v_pk_mul_f32 v[38:39], v[4:5], v[38:39]
	s_waitcnt lgkmcnt(0)
	v_add_f32_e32 v11, v18, v19
	v_lshl_add_u64 v[18:19], s[46:47], 0, v[52:53]
	global_load_dwordx4 v[30:33], v[18:19], off offset:16
	global_load_dwordx4 v[76:79], v[18:19], off
	v_pk_mul_f32 v[18:19], v[6:7], v[40:41]
	v_pk_mul_f32 v[36:37], v[2:3], v[36:37]
	v_pk_mov_b32 v[40:41], v[38:39], v[18:19] op_sel:[1,0]
	v_mov_b32_e32 v39, v19
	v_pk_mul_f32 v[34:35], v[0:1], v[34:35]
	v_pk_add_f32 v[18:19], v[40:41], v[38:39]
	v_mov_b32_e32 v38, v36
	v_mov_b32_e32 v39, v34
	v_mov_b32_e32 v34, v37
	v_pk_add_f32 v[34:35], v[38:39], v[34:35]
	v_add_f32_e32 v18, v18, v19
	v_add_f32_e32 v18, v18, v35
	v_mul_f32_e32 v47, v12, v128
	s_nop 1
	v_mov_b32_dpp v12, v11 row_mirror row_mask:0xf bank_mask:0xf
	s_nop 1
	v_mov_b32_dpp v12, v12 row_half_mirror row_mask:0xf bank_mask:0xf
	v_add_f32_e32 v18, v34, v18
	s_nop 1
	v_mov_b32_dpp v19, v18 quad_perm:[1,0,3,2] row_mask:0xf bank_mask:0xf
	v_pk_mul_f32 v[34:35], v[16:17], v[128:129]
	s_waitcnt vmcnt(4)
	v_pk_mul_f32 v[38:39], v[4:5], v[62:63]
	s_waitcnt lgkmcnt(1)
	v_add_f32_e32 v11, v11, v12
	v_pk_fma_f32 v[16:17], v[16:17], v[128:129], v[34:35] op_sel_hi:[1,1,0]
	v_max_f32_e32 v46, v25, v11
	s_waitcnt lgkmcnt(0)
	v_add_f32_e32 v12, v18, v19
	s_nop 1
	v_mov_b32_dpp v16, v12 quad_perm:[2,3,0,1] row_mask:0xf bank_mask:0xf
	v_sub_f32_e32 v18, v25, v46
	v_exp_f32_e32 v37, v18
	v_pk_mul_f32 v[18:19], v[6:7], v[64:65]
	v_sub_f32_e32 v11, v11, v46
	v_pk_mov_b32 v[40:41], v[38:39], v[18:19] op_sel:[1,0]
	v_mov_b32_e32 v39, v19
	v_pk_add_f32 v[18:19], v[40:41], v[38:39]
	v_pk_mul_f32 v[38:39], v[2:3], v[60:61]
	v_pk_mul_f32 v[40:41], v[0:1], v[58:59]
	v_mov_b32_e32 v52, v38
	v_mov_b32_e32 v53, v40
	v_mov_b32_e32 v40, v39
	v_exp_f32_e32 v36, v11
	s_waitcnt lgkmcnt(0)
	v_add_f32_e32 v11, v12, v16
	v_pk_add_f32 v[38:39], v[52:53], v[40:41]
	v_add_f32_e32 v16, v18, v19
	v_add_f32_e32 v16, v16, v39
	v_add_f32_e32 v18, v38, v16
	s_nop 1
	v_mov_b32_dpp v19, v18 quad_perm:[1,0,3,2] row_mask:0xf bank_mask:0xf
	s_nop 1
	v_mov_b32_dpp v12, v11 row_half_mirror row_mask:0xf bank_mask:0xf
	s_nop 1
	v_mov_b32_dpp v12, v12 quad_perm:[3,2,1,0] row_mask:0xf bank_mask:0xf
	v_mov_b32_e32 v16, v45
	v_mul_f32_e32 v25, v54, v36
	v_mov_b32_e32 v54, v55
	s_waitcnt lgkmcnt(1)
	v_add_f32_e32 v18, v18, v19
	s_nop 1
	v_mov_b32_dpp v19, v18 quad_perm:[2,3,0,1] row_mask:0xf bank_mask:0xf
	s_waitcnt lgkmcnt(1)
	v_add_f32_e32 v11, v11, v12
	s_nop 1
	v_mov_b32_dpp v38, v11 row_mirror row_mask:0xf bank_mask:0xf
	s_nop 1
	v_mov_b32_dpp v38, v38 row_half_mirror row_mask:0xf bank_mask:0xf
	v_mul_f32_e32 v12, v45, v36
	v_pk_fma_f32 v[16:17], v[16:17], v[36:37], v[12:13] op_sel_hi:[1,1,0]
	s_waitcnt lgkmcnt(1)
	v_add_f32_e32 v12, v18, v19
	s_nop 1
	v_mov_b32_dpp v16, v12 row_half_mirror row_mask:0xf bank_mask:0xf
	s_nop 1
	v_mov_b32_dpp v16, v16 quad_perm:[3,2,1,0] row_mask:0xf bank_mask:0xf
	s_waitcnt lgkmcnt(1)
	v_add_f32_e32 v11, v11, v38
	v_max_f32_e32 v40, v46, v11
	v_sub_f32_e32 v11, v11, v40
	v_sub_f32_e32 v18, v46, v40
	v_exp_f32_e32 v38, v11
	s_waitcnt lgkmcnt(0)
	v_add_f32_e32 v11, v12, v16
	v_exp_f32_e32 v39, v18
	s_nop 1
	v_mov_b32_dpp v18, v11 row_mirror row_mask:0xf bank_mask:0xf
	s_nop 1
	v_mov_b32_dpp v18, v18 row_half_mirror row_mask:0xf bank_mask:0xf
	s_waitcnt vmcnt(3)
	v_mov_b32_e32 v16, v23
	v_mul_f32_e32 v12, v23, v38
	v_pk_fma_f32 v[16:17], v[16:17], v[38:39], v[12:13] op_sel_hi:[1,1,0]
	v_mov_b32_e32 v46, v128
	s_waitcnt lgkmcnt(0)
	v_add_f32_e32 v11, v11, v18
	v_max_f32_e32 v18, v40, v11
	v_sub_f32_e32 v11, v11, v18
	v_sub_f32_e32 v12, v40, v18
	v_exp_f32_e32 v40, v11
	v_exp_f32_e32 v12, v12
	s_waitcnt vmcnt(2)
	v_mul_f32_e32 v19, v26, v38
	v_pk_add_f32 v[46:47], v[46:47], v[34:35] op_sel:[0,1]
	v_mov_b32_e32 v16, v37
	v_mov_b32_e32 v37, v25
	v_pk_fma_f32 v[46:47], v[46:47], v[16:17], v[36:37] op_sel_hi:[1,0,1]
	v_mov_b32_e32 v26, v39
	v_mov_b32_e32 v39, v19
	v_pk_fma_f32 v[46:47], v[46:47], v[26:27], v[38:39] op_sel_hi:[1,0,1]
	s_waitcnt vmcnt(0)
	v_mul_f32_e32 v41, v76, v40
	v_pk_fma_f32 v[52:53], v[46:47], v[12:13], v[40:41] op_sel_hi:[1,0,1]
	v_mov_b32_e32 v46, v13
	v_mov_b32_e32 v47, v14
	v_pk_fma_f32 v[46:47], v[46:47], v[128:129], v[34:35] op_sel:[0,0,1] op_sel_hi:[1,0,1]
	v_mov_b32_e32 v55, v56
	v_pk_mul_f32 v[46:47], v[46:47], v[16:17] op_sel_hi:[1,0]
	v_pk_mov_b32 v[14:15], v[14:15], v[8:9] op_sel:[1,0]
	v_pk_fma_f32 v[46:47], v[54:55], v[36:37], v[46:47] op_sel_hi:[1,0,1]
	v_mov_b32_e32 v54, v27
	v_pk_mul_f32 v[46:47], v[46:47], v[26:27] op_sel_hi:[1,0]
	v_mov_b32_e32 v55, v28
	v_pk_fma_f32 v[46:47], v[54:55], v[38:39], v[46:47] op_sel_hi:[1,0,1]
	v_mov_b32_e32 v8, v9
	v_mov_b32_e32 v9, v10
	v_pk_mul_f32 v[46:47], v[46:47], v[12:13] op_sel_hi:[1,0]
	v_mov_b32_e32 v54, v77
	v_mov_b32_e32 v55, v78
	v_pk_fma_f32 v[14:15], v[14:15], v[128:129], v[34:35] op_sel:[0,0,1] op_sel_hi:[1,0,1]
	v_pk_fma_f32 v[8:9], v[8:9], v[128:129], v[34:35] op_sel:[0,0,1] op_sel_hi:[1,0,1]
	v_pk_fma_f32 v[58:59], v[54:55], v[40:41], v[46:47] op_sel_hi:[1,0,1]
	v_pk_mul_f32 v[14:15], v[14:15], v[16:17] op_sel_hi:[1,0]
	v_pk_mov_b32 v[46:47], v[56:57], v[42:43] op_sel:[1,0]
	v_pk_mul_f32 v[8:9], v[8:9], v[16:17] op_sel_hi:[1,0]
	v_mov_b32_e32 v10, v43
	v_mov_b32_e32 v11, v44
	v_pk_fma_f32 v[14:15], v[46:47], v[36:37], v[14:15] op_sel_hi:[1,0,1]
	v_pk_fma_f32 v[8:9], v[10:11], v[36:37], v[8:9] op_sel_hi:[1,0,1]
	v_pk_mul_f32 v[14:15], v[14:15], v[26:27] op_sel_hi:[1,0]
	v_pk_mov_b32 v[28:29], v[28:29], v[20:21] op_sel:[1,0]
	v_pk_mul_f32 v[8:9], v[8:9], v[26:27] op_sel_hi:[1,0]
	v_mov_b32_e32 v10, v21
	v_mov_b32_e32 v11, v22
	v_pk_fma_f32 v[14:15], v[28:29], v[38:39], v[14:15] op_sel_hi:[1,0,1]
	v_pk_fma_f32 v[8:9], v[10:11], v[38:39], v[8:9] op_sel_hi:[1,0,1]
	v_pk_mul_f32 v[14:15], v[14:15], v[12:13] op_sel_hi:[1,0]
	v_pk_mov_b32 v[28:29], v[78:79], v[30:31] op_sel:[1,0]
	v_pk_mul_f32 v[8:9], v[8:9], v[12:13] op_sel_hi:[1,0]
	v_mov_b32_e32 v10, v31
	v_mov_b32_e32 v11, v32
	v_pk_fma_f32 v[56:57], v[28:29], v[40:41], v[14:15] op_sel_hi:[1,0,1]
	v_pk_fma_f32 v[54:55], v[10:11], v[40:41], v[8:9] op_sel_hi:[1,0,1]
	v_mov_b32_e32 v16, v33
	v_mov_b32_e32 v41, v12
	v_mul_f32_e32 v8, v17, v12
	v_pk_fma_f32 v[16:17], v[16:17], v[40:41], v[8:9] op_sel_hi:[1,1,0]
	s_and_saveexec_b64 s[8:9], s[38:39]
	s_cbranch_execz .LBB0_568
	global_load_dwordx4 v[8:11], v[48:49], off
	global_load_dwordx4 v[12:15], v[48:49], off offset:16
	global_load_dwordx4 v[20:23], v[48:49], off offset:2048
	global_load_dwordx4 v[26:29], v[48:49], off offset:2064
	s_waitcnt vmcnt(3)
	v_pk_mul_f32 v[6:7], v[6:7], v[10:11]
	v_pk_mul_f32 v[4:5], v[4:5], v[8:9]
	s_waitcnt vmcnt(2)
	v_pk_mul_f32 v[2:3], v[2:3], v[14:15]
	v_pk_mul_f32 v[0:1], v[0:1], v[12:13]
	v_pk_mov_b32 v[8:9], v[4:5], v[6:7] op_sel:[1,0]
	v_mov_b32_e32 v5, v7
	v_mov_b32_e32 v6, v2
	v_mov_b32_e32 v7, v0
	v_mov_b32_e32 v0, v3
	v_pk_add_f32 v[2:3], v[8:9], v[4:5]
	v_pk_add_f32 v[0:1], v[6:7], v[0:1]
	v_add_f32_e32 v2, v2, v3
	v_add_f32_e32 v1, v2, v1
	v_add_f32_e32 v0, v0, v1
	s_nop 1
	v_mov_b32_dpp v1, v0 quad_perm:[1,0,3,2] row_mask:0xf bank_mask:0xf
	v_max_f32_e32 v7, v18, v18
	s_waitcnt vmcnt(1)
	v_mov_b32_e32 v3, v22
	s_waitcnt vmcnt(0)
	v_pk_mov_b32 v[4:5], v[22:23], v[26:27] op_sel:[1,0]
	v_mov_b32_e32 v6, v27
	s_waitcnt lgkmcnt(0)
	v_add_f32_e32 v0, v0, v1
	s_nop 1
	v_mov_b32_dpp v1, v0 quad_perm:[2,3,0,1] row_mask:0xf bank_mask:0xf
	s_waitcnt lgkmcnt(0)
	v_add_f32_e32 v0, v0, v1
	s_nop 1
	v_mov_b32_dpp v2, v0 row_half_mirror row_mask:0xf bank_mask:0xf
	s_nop 1
	v_mov_b32_dpp v2, v2 quad_perm:[3,2,1,0] row_mask:0xf bank_mask:0xf
	v_mov_b32_e32 v1, v16
	s_waitcnt lgkmcnt(0)
	v_add_f32_e32 v0, v0, v2
	s_nop 1
	v_mov_b32_dpp v8, v0 row_mirror row_mask:0xf bank_mask:0xf
	s_nop 1
	v_mov_b32_dpp v8, v8 row_half_mirror row_mask:0xf bank_mask:0xf
	v_mov_b32_e32 v2, v21
	s_waitcnt lgkmcnt(0)
	v_add_f32_e32 v0, v0, v8
	v_max_f32_e32 v11, v7, v0
	v_sub_f32_e32 v7, v18, v11
	v_sub_f32_e32 v0, v0, v11
	v_exp_f32_e32 v8, v0
	v_exp_f32_e32 v10, v7
	v_mov_b32_e32 v7, v28
	v_mov_b32_e32 v0, v29
	v_mul_f32_e32 v9, v20, v8
	v_pk_mul_f32 v[12:13], v[58:59], v[10:11] op_sel_hi:[1,0]
	v_pk_mul_f32 v[14:15], v[56:57], v[10:11] op_sel_hi:[1,0]
	v_pk_mul_f32 v[16:17], v[54:55], v[10:11] op_sel_hi:[1,0]
	v_pk_fma_f32 v[52:53], v[52:53], v[10:11], v[8:9] op_sel_hi:[1,0,1]
	v_pk_fma_f32 v[58:59], v[2:3], v[8:9], v[12:13] op_sel_hi:[1,0,1]
	v_pk_fma_f32 v[56:57], v[4:5], v[8:9], v[14:15] op_sel_hi:[1,0,1]
	v_pk_fma_f32 v[54:55], v[6:7], v[8:9], v[16:17] op_sel_hi:[1,0,1]
	v_mov_b32_e32 v9, v10
	v_pk_mul_f32 v[0:1], v[0:1], v[8:9]
	v_mov_b32_e32 v18, v11
	v_add_f32_e32 v16, v0, v1
.LBB0_568:
	s_or_b64 exec, exec, s[8:9]
	v_add_u32_e32 v78, 1, v24
	v_lshlrev_b32_e32 v8, 2, v78
	v_sub_u32_e32 v8, 0x800, v8
	v_ashrrev_i32_e32 v9, 31, v8
	v_lshlrev_b64 v[8:9], 9, v[8:9]
	v_readlane_b32 s40, v241, 8
	v_lshl_add_u64 v[8:9], v[8:9], 0, s[6:7]
	v_readlane_b32 s48, v241, 16
	v_readlane_b32 s49, v241, 17
	s_mov_b64 s[8:9], 0x1000
	v_add_co_u32_e32 v2, vcc, 0x1000, v50
	v_or_b32_e32 v8, v8, v74
	v_readlane_b32 s50, v241, 18
	v_readlane_b32 s51, v241, 19
	v_readlane_b32 s52, v241, 20
	v_readlane_b32 s53, v241, 21
	v_readlane_b32 s54, v241, 22
	v_readlane_b32 s55, v241, 23
	s_mov_b64 s[12:13], s[48:49]
	v_lshl_add_u64 v[0:1], v[50:51], 0, s[8:9]
	v_addc_co_u32_e32 v3, vcc, 0, v51, vcc
	v_lshlrev_b64 v[8:9], 2, v[8:9]
	s_mov_b64 s[14:15], s[50:51]
	global_load_dwordx4 v[4:7], v[2:3], off
	s_nop 0
	global_load_dwordx4 v[0:3], v[0:1], off offset:16
	v_lshl_add_u64 v[10:11], s[12:13], 0, v[8:9]
	v_lshl_add_u64 v[12:13], s[14:15], 0, v[8:9]
	v_add_u32_e32 v77, 33, v24
	v_add_u32_e32 v76, 0x41, v24
	v_add_u32_e32 v75, 0x61, v24
	global_load_dwordx4 v[20:23], v[10:11], off offset:16
	global_load_dwordx4 v[24:27], v[10:11], off
	s_nop 0
	global_load_dwordx4 v[8:11], v[12:13], off offset:16
	s_nop 0
	global_load_dwordx4 v[12:15], v[12:13], off
	v_readlane_b32 s41, v241, 9
	v_readlane_b32 s42, v241, 10
	v_readlane_b32 s43, v241, 11
	v_readlane_b32 s44, v241, 12
	v_readlane_b32 s45, v241, 13
	v_readlane_b32 s46, v241, 14
	v_readlane_b32 s47, v241, 15
	s_mov_b64 s[16:17], s[52:53]
	s_mov_b64 s[18:19], s[54:55]
	s_waitcnt vmcnt(3)
	v_pk_mul_f32 v[22:23], v[2:3], v[22:23]
	s_waitcnt vmcnt(2)
	v_pk_mul_f32 v[26:27], v[6:7], v[26:27]
	v_pk_mul_f32 v[24:25], v[4:5], v[24:25]
	v_pk_mul_f32 v[20:21], v[0:1], v[20:21]
	v_pk_mov_b32 v[28:29], v[24:25], v[26:27] op_sel:[1,0]
	v_mov_b32_e32 v25, v27
	v_pk_add_f32 v[24:25], v[28:29], v[24:25]
	v_mov_b32_e32 v26, v22
	v_mov_b32_e32 v27, v20
	v_mov_b32_e32 v20, v23
	v_pk_add_f32 v[20:21], v[26:27], v[20:21]
	v_add_f32_e32 v17, v24, v25
	v_add_f32_e32 v17, v17, v21
	v_add_f32_e32 v17, v20, v17
	s_nop 1
	v_mov_b32_dpp v19, v17 quad_perm:[1,0,3,2] row_mask:0xf bank_mask:0xf
	s_waitcnt lgkmcnt(0)
	v_add_f32_e32 v17, v17, v19
	s_nop 1
	v_mov_b32_dpp v19, v17 quad_perm:[2,3,0,1] row_mask:0xf bank_mask:0xf
	s_waitcnt lgkmcnt(0)
	v_add_f32_e32 v17, v17, v19
	s_nop 1
	v_mov_b32_dpp v19, v17 row_half_mirror row_mask:0xf bank_mask:0xf
	s_nop 1
	v_mov_b32_dpp v19, v19 quad_perm:[3,2,1,0] row_mask:0xf bank_mask:0xf
	s_waitcnt lgkmcnt(0)
	v_add_f32_e32 v17, v17, v19
	s_nop 1
	v_mov_b32_dpp v19, v17 row_mirror row_mask:0xf bank_mask:0xf
	s_nop 1
	v_mov_b32_dpp v19, v19 row_half_mirror row_mask:0xf bank_mask:0xf
	s_waitcnt lgkmcnt(0)
	v_add_f32_e32 v17, v17, v19
	v_max_f32_e32 v19, v18, v18
	v_max_f32_e32 v36, v19, v17
	v_sub_f32_e32 v17, v17, v36
	v_sub_f32_e32 v18, v18, v36
	v_exp_f32_e32 v60, v17
	v_exp_f32_e32 v61, v18
	s_waitcnt vmcnt(1)
	v_mov_b32_e32 v18, v11
	v_mov_b32_e32 v19, v16
	v_mul_f32_e32 v16, v11, v60
	v_lshlrev_b32_e32 v11, 2, v77
	v_pk_fma_f32 v[32:33], v[18:19], v[60:61], v[16:17] op_sel_hi:[1,1,0]
	v_sub_u32_e32 v16, 0x800, v11
	v_ashrrev_i32_e32 v17, 31, v16
	v_lshlrev_b64 v[16:17], 9, v[16:17]
	v_lshl_add_u64 v[16:17], v[16:17], 0, s[6:7]
	v_or_b32_e32 v16, v16, v74
	v_lshlrev_b64 v[16:17], 2, v[16:17]
	v_lshl_add_u64 v[18:19], s[12:13], 0, v[16:17]
	v_lshl_add_u64 v[20:21], s[14:15], 0, v[16:17]
	global_load_dwordx4 v[24:27], v[18:19], off offset:16
	global_load_dwordx4 v[28:31], v[18:19], off
	s_nop 0
	global_load_dwordx4 v[16:19], v[20:21], off offset:16
	s_nop 0
	global_load_dwordx4 v[20:23], v[20:21], off
	s_waitcnt vmcnt(4)
	v_mul_f32_e32 v12, v12, v60
	s_waitcnt vmcnt(3)
	v_pk_mul_f32 v[26:27], v[2:3], v[26:27]
	s_waitcnt vmcnt(2)
	v_pk_mul_f32 v[30:31], v[6:7], v[30:31]
	v_pk_mul_f32 v[28:29], v[4:5], v[28:29]
	v_pk_mul_f32 v[24:25], v[0:1], v[24:25]
	v_pk_mov_b32 v[34:35], v[28:29], v[30:31] op_sel:[1,0]
	v_mov_b32_e32 v29, v31
	v_pk_add_f32 v[28:29], v[34:35], v[28:29]
	v_mov_b32_e32 v30, v26
	v_mov_b32_e32 v31, v24
	v_mov_b32_e32 v24, v27
	v_pk_add_f32 v[24:25], v[30:31], v[24:25]
	v_add_f32_e32 v11, v28, v29
	v_add_f32_e32 v11, v11, v25
	v_add_f32_e32 v11, v24, v11
	s_nop 1
	v_mov_b32_dpp v24, v11 quad_perm:[1,0,3,2] row_mask:0xf bank_mask:0xf
	s_waitcnt vmcnt(1)
	v_mov_b32_e32 v32, v19
	s_waitcnt lgkmcnt(0)
	v_add_f32_e32 v11, v11, v24
	s_nop 1
	v_mov_b32_dpp v24, v11 quad_perm:[2,3,0,1] row_mask:0xf bank_mask:0xf
	s_waitcnt lgkmcnt(0)
	v_add_f32_e32 v11, v11, v24
	s_nop 1
	v_mov_b32_dpp v24, v11 row_half_mirror row_mask:0xf bank_mask:0xf
	s_nop 1
	v_mov_b32_dpp v24, v24 quad_perm:[3,2,1,0] row_mask:0xf bank_mask:0xf
	s_waitcnt lgkmcnt(0)
	v_add_f32_e32 v11, v11, v24
	s_nop 1
	v_mov_b32_dpp v24, v11 row_mirror row_mask:0xf bank_mask:0xf
	s_nop 1
	v_mov_b32_dpp v24, v24 row_half_mirror row_mask:0xf bank_mask:0xf
	s_waitcnt lgkmcnt(0)
	v_add_f32_e32 v11, v11, v24
	v_max_f32_e32 v44, v36, v11
	v_sub_f32_e32 v11, v11, v44
	v_exp_f32_e32 v62, v11
	v_sub_f32_e32 v24, v36, v44
	v_exp_f32_e32 v63, v24
	s_waitcnt vmcnt(0)
	v_mul_f32_e32 v11, v20, v62
	v_mul_f32_e32 v20, v19, v62
	v_lshlrev_b32_e32 v19, 2, v76
	v_sub_u32_e32 v24, 0x800, v19
	v_ashrrev_i32_e32 v25, 31, v24
	v_lshlrev_b64 v[24:25], 9, v[24:25]
	v_lshl_add_u64 v[24:25], v[24:25], 0, s[6:7]
	v_or_b32_e32 v24, v24, v74
	v_lshlrev_b64 v[24:25], 2, v[24:25]
	v_lshl_add_u64 v[26:27], s[12:13], 0, v[24:25]
	v_lshl_add_u64 v[28:29], s[14:15], 0, v[24:25]
	v_pk_fma_f32 v[40:41], v[32:33], v[62:63], v[20:21] op_sel_hi:[1,1,0]
	global_load_dwordx4 v[32:35], v[26:27], off offset:16
	global_load_dwordx4 v[36:39], v[26:27], off
	s_nop 0
	global_load_dwordx4 v[24:27], v[28:29], off offset:16
	s_nop 0
	global_load_dwordx4 v[28:31], v[28:29], off
	s_waitcnt vmcnt(3)
	v_pk_mul_f32 v[34:35], v[2:3], v[34:35]
	s_waitcnt vmcnt(2)
	v_pk_mul_f32 v[38:39], v[6:7], v[38:39]
	v_pk_mul_f32 v[36:37], v[4:5], v[36:37]
	v_pk_mul_f32 v[32:33], v[0:1], v[32:33]
	v_pk_mov_b32 v[42:43], v[36:37], v[38:39] op_sel:[1,0]
	v_mov_b32_e32 v37, v39
	v_pk_add_f32 v[36:37], v[42:43], v[36:37]
	v_mov_b32_e32 v38, v34
	v_mov_b32_e32 v39, v32
	v_mov_b32_e32 v32, v35
	v_pk_add_f32 v[32:33], v[38:39], v[32:33]
	v_add_f32_e32 v19, v36, v37
	v_add_f32_e32 v19, v19, v33
	v_add_f32_e32 v19, v32, v19
	s_nop 1
	v_mov_b32_dpp v20, v19 quad_perm:[1,0,3,2] row_mask:0xf bank_mask:0xf
	s_waitcnt vmcnt(1)
	v_mov_b32_e32 v40, v27
	s_waitcnt lgkmcnt(0)
	v_add_f32_e32 v19, v19, v20
	s_nop 1
	v_mov_b32_dpp v20, v19 quad_perm:[2,3,0,1] row_mask:0xf bank_mask:0xf
	s_waitcnt lgkmcnt(0)
	v_add_f32_e32 v19, v19, v20
	s_nop 1
	v_mov_b32_dpp v20, v19 row_half_mirror row_mask:0xf bank_mask:0xf
	s_nop 1
	v_mov_b32_dpp v20, v20 quad_perm:[3,2,1,0] row_mask:0xf bank_mask:0xf
	s_waitcnt lgkmcnt(0)
	v_add_f32_e32 v19, v19, v20
	s_nop 1
	v_mov_b32_dpp v20, v19 row_mirror row_mask:0xf bank_mask:0xf
	s_nop 1
	v_mov_b32_dpp v20, v20 row_half_mirror row_mask:0xf bank_mask:0xf
	s_waitcnt lgkmcnt(0)
	v_add_f32_e32 v19, v19, v20
	v_max_f32_e32 v20, v44, v19
	v_sub_f32_e32 v19, v19, v20
	v_exp_f32_e32 v66, v19
	v_sub_f32_e32 v32, v44, v20
	v_exp_f32_e32 v67, v32
	s_waitcnt vmcnt(0)
	v_mul_f32_e32 v19, v28, v66
	v_mul_f32_e32 v28, v27, v66
	v_lshlrev_b32_e32 v27, 2, v75
	v_sub_u32_e32 v32, 0x800, v27
	v_ashrrev_i32_e32 v33, 31, v32
	v_lshlrev_b64 v[32:33], 9, v[32:33]
	v_lshl_add_u64 v[32:33], v[32:33], 0, s[6:7]
	v_or_b32_e32 v32, v32, v74
	v_lshlrev_b64 v[32:33], 2, v[32:33]
	v_lshl_add_u64 v[34:35], s[12:13], 0, v[32:33]
	v_lshl_add_u64 v[36:37], s[14:15], 0, v[32:33]
	v_pk_fma_f32 v[64:65], v[40:41], v[66:67], v[28:29] op_sel_hi:[1,1,0]
	global_load_dwordx4 v[40:43], v[34:35], off offset:16
	global_load_dwordx4 v[44:47], v[34:35], off
	s_nop 0
	global_load_dwordx4 v[32:35], v[36:37], off offset:16
	s_nop 0
	global_load_dwordx4 v[36:39], v[36:37], off
	s_waitcnt vmcnt(3)
	v_pk_mul_f32 v[42:43], v[2:3], v[42:43]
	s_waitcnt vmcnt(2)
	v_pk_mul_f32 v[46:47], v[6:7], v[46:47]
	v_pk_mul_f32 v[44:45], v[4:5], v[44:45]
	v_pk_mul_f32 v[40:41], v[0:1], v[40:41]
	v_pk_mov_b32 v[80:81], v[44:45], v[46:47] op_sel:[1,0]
	v_mov_b32_e32 v45, v47
	v_pk_add_f32 v[44:45], v[80:81], v[44:45]
	v_mov_b32_e32 v46, v42
	v_mov_b32_e32 v47, v40
	v_mov_b32_e32 v40, v43
	v_pk_add_f32 v[40:41], v[46:47], v[40:41]
	v_add_f32_e32 v27, v44, v45
	v_add_f32_e32 v27, v27, v41
	v_add_f32_e32 v27, v40, v27
	s_nop 1
	v_mov_b32_dpp v28, v27 quad_perm:[1,0,3,2] row_mask:0xf bank_mask:0xf
	v_mov_b32_e32 v44, v63
	v_mov_b32_e32 v63, v11
	v_mov_b32_e32 v46, v67
	v_mov_b32_e32 v67, v19
	s_waitcnt lgkmcnt(0)
	v_add_f32_e32 v27, v27, v28
	s_nop 1
	v_mov_b32_dpp v28, v27 quad_perm:[2,3,0,1] row_mask:0xf bank_mask:0xf
	v_mov_b32_e32 v11, v18
	s_waitcnt vmcnt(1)
	v_mov_b32_e32 v64, v35
	s_waitcnt lgkmcnt(0)
	v_add_f32_e32 v27, v27, v28
	s_nop 1
	v_mov_b32_dpp v28, v27 row_half_mirror row_mask:0xf bank_mask:0xf
	s_nop 1
	v_mov_b32_dpp v28, v28 quad_perm:[3,2,1,0] row_mask:0xf bank_mask:0xf
	s_waitcnt lgkmcnt(0)
	v_add_f32_e32 v27, v27, v28
	s_nop 1
	v_mov_b32_dpp v28, v27 row_mirror row_mask:0xf bank_mask:0xf
	s_nop 1
	v_mov_b32_dpp v28, v28 row_half_mirror row_mask:0xf bank_mask:0xf
	s_waitcnt lgkmcnt(0)
	v_add_f32_e32 v28, v27, v28
	v_max_f32_e32 v27, v20, v28
	v_sub_f32_e32 v28, v28, v27
	v_exp_f32_e32 v42, v28
	v_mov_b32_e32 v28, v61
	v_mov_b32_e32 v61, v12
	v_pk_fma_f32 v[40:41], v[52:53], v[28:29], v[60:61] op_sel_hi:[1,0,1]
	v_pk_mul_f32 v[52:53], v[58:59], v[28:29] op_sel_hi:[1,0]
	v_mov_b32_e32 v12, v13
	v_mov_b32_e32 v13, v14
	v_sub_f32_e32 v20, v20, v27
	v_pk_fma_f32 v[12:13], v[12:13], v[60:61], v[52:53] op_sel_hi:[1,0,1]
	v_exp_f32_e32 v20, v20
	v_pk_mul_f32 v[12:13], v[12:13], v[44:45] op_sel_hi:[1,0]
	v_mov_b32_e32 v52, v21
	v_mov_b32_e32 v53, v22
	v_pk_fma_f32 v[12:13], v[52:53], v[62:63], v[12:13] op_sel_hi:[1,0,1]
	v_mov_b32_e32 v52, v29
	v_pk_mul_f32 v[12:13], v[12:13], v[46:47] op_sel_hi:[1,0]
	v_mov_b32_e32 v53, v30
	v_pk_fma_f32 v[12:13], v[52:53], v[66:67], v[12:13] op_sel_hi:[1,0,1]
	s_waitcnt vmcnt(0)
	v_mul_f32_e32 v43, v36, v42
	v_pk_mul_f32 v[12:13], v[12:13], v[20:21] op_sel_hi:[1,0]
	v_mov_b32_e32 v36, v37
	v_mov_b32_e32 v37, v38
	v_pk_fma_f32 v[12:13], v[36:37], v[42:43], v[12:13] op_sel_hi:[1,0,1]
	v_pk_mul_f32 v[36:37], v[56:57], v[28:29] op_sel_hi:[1,0]
	v_pk_mov_b32 v[14:15], v[14:15], v[8:9] op_sel:[1,0]
	v_pk_mov_b32 v[22:23], v[22:23], v[16:17] op_sel:[1,0]
	v_pk_fma_f32 v[14:15], v[14:15], v[60:61], v[36:37] op_sel_hi:[1,0,1]
	v_mov_b32_e32 v8, v9
	v_pk_mul_f32 v[14:15], v[14:15], v[44:45] op_sel_hi:[1,0]
	v_mov_b32_e32 v9, v10
	v_pk_fma_f32 v[14:15], v[22:23], v[62:63], v[14:15] op_sel_hi:[1,0,1]
	v_pk_mov_b32 v[22:23], v[30:31], v[24:25] op_sel:[1,0]
	v_pk_mul_f32 v[14:15], v[14:15], v[46:47] op_sel_hi:[1,0]
	v_mov_b32_e32 v10, v17
	v_pk_fma_f32 v[14:15], v[22:23], v[66:67], v[14:15] op_sel_hi:[1,0,1]
	v_pk_mov_b32 v[22:23], v[38:39], v[32:33] op_sel:[1,0]
	v_pk_mul_f32 v[14:15], v[14:15], v[20:21] op_sel_hi:[1,0]
	v_pk_fma_f32 v[40:41], v[40:41], v[44:45], v[62:63] op_sel_hi:[1,0,1]
	v_pk_fma_f32 v[14:15], v[22:23], v[42:43], v[14:15] op_sel_hi:[1,0,1]
	v_pk_mul_f32 v[22:23], v[54:55], v[28:29] op_sel_hi:[1,0]
	v_pk_fma_f32 v[40:41], v[40:41], v[46:47], v[66:67] op_sel_hi:[1,0,1]
	v_pk_fma_f32 v[8:9], v[8:9], v[60:61], v[22:23] op_sel_hi:[1,0,1]
	v_pk_fma_f32 v[40:41], v[40:41], v[20:21], v[42:43] op_sel_hi:[1,0,1]
	v_pk_mul_f32 v[8:9], v[8:9], v[44:45] op_sel_hi:[1,0]
	s_nop 0
	v_pk_fma_f32 v[8:9], v[10:11], v[62:63], v[8:9] op_sel_hi:[1,0,1]
	v_mov_b32_e32 v10, v25
	v_pk_mul_f32 v[8:9], v[8:9], v[46:47] op_sel_hi:[1,0]
	v_mov_b32_e32 v11, v26
	v_pk_fma_f32 v[8:9], v[10:11], v[66:67], v[8:9] op_sel_hi:[1,0,1]
	v_mov_b32_e32 v10, v33
	v_pk_mul_f32 v[8:9], v[8:9], v[20:21] op_sel_hi:[1,0]
	v_mov_b32_e32 v11, v34
	v_pk_fma_f32 v[8:9], v[10:11], v[42:43], v[8:9] op_sel_hi:[1,0,1]
	v_mov_b32_e32 v43, v20
	v_mul_f32_e32 v10, v65, v20
	v_pk_fma_f32 v[10:11], v[64:65], v[42:43], v[10:11] op_sel_hi:[1,1,0]
	s_and_saveexec_b64 s[8:9], s[38:39]
	s_cbranch_execz .LBB0_570
	global_load_dwordx4 v[16:19], v[48:49], off
	global_load_dwordx4 v[20:23], v[48:49], off offset:16
	global_load_dwordx4 v[28:31], v[48:49], off offset:2048
	global_load_dwordx4 v[32:35], v[48:49], off offset:2064
	s_waitcnt vmcnt(3)
	v_pk_mul_f32 v[6:7], v[6:7], v[18:19]
	v_pk_mul_f32 v[4:5], v[4:5], v[16:17]
	s_waitcnt vmcnt(2)
	v_pk_mul_f32 v[2:3], v[2:3], v[22:23]
	v_pk_mul_f32 v[0:1], v[0:1], v[20:21]
	v_pk_mov_b32 v[16:17], v[4:5], v[6:7] op_sel:[1,0]
	v_mov_b32_e32 v5, v7
	v_mov_b32_e32 v6, v2
	v_mov_b32_e32 v7, v0
	v_mov_b32_e32 v0, v3
	v_pk_add_f32 v[2:3], v[16:17], v[4:5]
	v_pk_add_f32 v[0:1], v[6:7], v[0:1]
	v_add_f32_e32 v2, v2, v3
	v_add_f32_e32 v1, v2, v1
	v_add_f32_e32 v0, v0, v1
	s_nop 1
	v_mov_b32_dpp v1, v0 quad_perm:[1,0,3,2] row_mask:0xf bank_mask:0xf
	v_max_f32_e32 v7, v27, v27
	s_waitcnt vmcnt(1)
	v_mov_b32_e32 v3, v30
	s_waitcnt vmcnt(0)
	v_pk_mov_b32 v[4:5], v[30:31], v[32:33] op_sel:[1,0]
	v_mov_b32_e32 v6, v33
	s_waitcnt lgkmcnt(0)
	v_add_f32_e32 v0, v0, v1
	s_nop 1
	v_mov_b32_dpp v1, v0 quad_perm:[2,3,0,1] row_mask:0xf bank_mask:0xf
	s_waitcnt lgkmcnt(0)
	v_add_f32_e32 v0, v0, v1
	s_nop 1
	v_mov_b32_dpp v2, v0 row_half_mirror row_mask:0xf bank_mask:0xf
	s_nop 1
	v_mov_b32_dpp v2, v2 quad_perm:[3,2,1,0] row_mask:0xf bank_mask:0xf
	v_mov_b32_e32 v1, v10
	s_waitcnt lgkmcnt(0)
	v_add_f32_e32 v0, v0, v2
	s_nop 1
	v_mov_b32_dpp v10, v0 row_mirror row_mask:0xf bank_mask:0xf
	s_nop 1
	v_mov_b32_dpp v10, v10 row_half_mirror row_mask:0xf bank_mask:0xf
	v_mov_b32_e32 v2, v29
	s_waitcnt lgkmcnt(0)
	v_add_f32_e32 v0, v0, v10
	v_max_f32_e32 v17, v7, v0
	v_sub_f32_e32 v7, v27, v17
	v_sub_f32_e32 v0, v0, v17
	v_exp_f32_e32 v10, v0
	v_exp_f32_e32 v16, v7
	v_mov_b32_e32 v7, v34
	v_mov_b32_e32 v0, v35
	v_mul_f32_e32 v11, v28, v10
	v_pk_mul_f32 v[12:13], v[12:13], v[16:17] op_sel_hi:[1,0]
	v_pk_mul_f32 v[14:15], v[14:15], v[16:17] op_sel_hi:[1,0]
	v_pk_mul_f32 v[8:9], v[8:9], v[16:17] op_sel_hi:[1,0]
	v_pk_fma_f32 v[40:41], v[40:41], v[16:17], v[10:11] op_sel_hi:[1,0,1]
	v_pk_fma_f32 v[12:13], v[2:3], v[10:11], v[12:13] op_sel_hi:[1,0,1]
	v_pk_fma_f32 v[14:15], v[4:5], v[10:11], v[14:15] op_sel_hi:[1,0,1]
	v_pk_fma_f32 v[8:9], v[6:7], v[10:11], v[8:9] op_sel_hi:[1,0,1]
	v_mov_b32_e32 v11, v16
	v_pk_mul_f32 v[0:1], v[0:1], v[10:11]
	v_mov_b32_e32 v27, v17
	v_add_f32_e32 v10, v0, v1
.LBB0_570:
	s_or_b64 exec, exec, s[8:9]
	v_lshlrev_b32_e32 v11, 4, v78
	v_sub_u32_e32 v16, 0x800, v11
	v_ashrrev_i32_e32 v17, 31, v16
	v_lshlrev_b64 v[16:17], 9, v[16:17]
	v_lshl_add_u64 v[16:17], v[16:17], 0, s[6:7]
	v_readlane_b32 s40, v241, 8
	s_mov_b64 s[8:9], 0x2000
	v_add_co_u32_e32 v2, vcc, 0x2000, v50
	v_or_b32_e32 v16, v16, v74
	v_readlane_b32 s48, v241, 16
	v_readlane_b32 s49, v241, 17
	v_lshl_add_u64 v[0:1], v[50:51], 0, s[8:9]
	v_addc_co_u32_e32 v3, vcc, 0, v51, vcc
	v_lshlrev_b64 v[16:17], 2, v[16:17]
	v_readlane_b32 s50, v241, 18
	v_readlane_b32 s51, v241, 19
	v_readlane_b32 s52, v241, 20
	v_readlane_b32 s53, v241, 21
	v_readlane_b32 s54, v241, 22
	v_readlane_b32 s55, v241, 23
	s_mov_b64 s[12:13], s[48:49]
	global_load_dwordx4 v[4:7], v[2:3], off
	s_nop 0
	global_load_dwordx4 v[0:3], v[0:1], off offset:16
	s_mov_b64 s[14:15], s[50:51]
	v_lshl_add_u64 v[20:21], s[12:13], 0, v[16:17]
	v_lshl_add_u64 v[24:25], s[14:15], 0, v[16:17]
	global_load_dwordx4 v[16:19], v[20:21], off offset:16
	s_nop 0
	global_load_dwordx4 v[20:23], v[20:21], off
	s_nop 0
	global_load_dwordx4 v[28:31], v[24:25], off offset:16
	global_load_dwordx4 v[32:35], v[24:25], off
	v_readlane_b32 s41, v241, 9
	v_readlane_b32 s42, v241, 10
	v_readlane_b32 s43, v241, 11
	v_readlane_b32 s44, v241, 12
	v_readlane_b32 s45, v241, 13
	v_readlane_b32 s46, v241, 14
	v_readlane_b32 s47, v241, 15
	s_mov_b64 s[16:17], s[52:53]
	s_mov_b64 s[18:19], s[54:55]
	s_waitcnt vmcnt(3)
	v_pk_mul_f32 v[18:19], v[2:3], v[18:19]
	s_waitcnt vmcnt(2)
	v_pk_mul_f32 v[22:23], v[6:7], v[22:23]
	v_pk_mul_f32 v[20:21], v[4:5], v[20:21]
	v_pk_mul_f32 v[16:17], v[0:1], v[16:17]
	v_pk_mov_b32 v[24:25], v[20:21], v[22:23] op_sel:[1,0]
	v_mov_b32_e32 v21, v23
	v_pk_add_f32 v[20:21], v[24:25], v[20:21]
	v_mov_b32_e32 v22, v18
	v_mov_b32_e32 v23, v16
	v_mov_b32_e32 v16, v19
	v_pk_add_f32 v[16:17], v[22:23], v[16:17]
	v_add_f32_e32 v11, v20, v21
	v_add_f32_e32 v11, v11, v17
	v_add_f32_e32 v11, v16, v11
	s_nop 1
	v_mov_b32_dpp v16, v11 quad_perm:[1,0,3,2] row_mask:0xf bank_mask:0xf
	s_waitcnt lgkmcnt(0)
	v_add_f32_e32 v11, v11, v16
	s_nop 1
	v_mov_b32_dpp v16, v11 quad_perm:[2,3,0,1] row_mask:0xf bank_mask:0xf
	s_waitcnt lgkmcnt(0)
	v_add_f32_e32 v11, v11, v16
	s_nop 1
	v_mov_b32_dpp v16, v11 row_half_mirror row_mask:0xf bank_mask:0xf
	s_nop 1
	v_mov_b32_dpp v16, v16 quad_perm:[3,2,1,0] row_mask:0xf bank_mask:0xf
	s_waitcnt lgkmcnt(0)
	v_add_f32_e32 v11, v11, v16
	s_nop 1
	v_mov_b32_dpp v16, v11 row_mirror row_mask:0xf bank_mask:0xf
	s_nop 1
	v_mov_b32_dpp v16, v16 row_half_mirror row_mask:0xf bank_mask:0xf
	s_waitcnt lgkmcnt(0)
	v_add_f32_e32 v11, v11, v16
	v_max_f32_e32 v16, v27, v27
	v_max_f32_e32 v38, v16, v11
	v_sub_f32_e32 v16, v27, v38
	v_exp_f32_e32 v46, v16
	v_lshlrev_b32_e32 v16, 4, v77
	v_sub_u32_e32 v16, 0x800, v16
	v_ashrrev_i32_e32 v17, 31, v16
	v_lshlrev_b64 v[16:17], 9, v[16:17]
	v_lshl_add_u64 v[16:17], v[16:17], 0, s[6:7]
	v_or_b32_e32 v16, v16, v74
	v_lshlrev_b64 v[16:17], 2, v[16:17]
	v_lshl_add_u64 v[20:21], s[12:13], 0, v[16:17]
	v_lshl_add_u64 v[36:37], s[14:15], 0, v[16:17]
	global_load_dwordx4 v[16:19], v[20:21], off offset:16
	s_nop 0
	global_load_dwordx4 v[20:23], v[20:21], off
	s_nop 0
	global_load_dwordx4 v[24:27], v[36:37], off offset:16
	global_load_dwordx4 v[42:45], v[36:37], off
	v_sub_f32_e32 v11, v11, v38
	v_exp_f32_e32 v50, v11
	s_waitcnt vmcnt(3)
	v_pk_mul_f32 v[18:19], v[2:3], v[18:19]
	s_waitcnt vmcnt(2)
	v_pk_mul_f32 v[22:23], v[6:7], v[22:23]
	v_pk_mul_f32 v[20:21], v[4:5], v[20:21]
	v_pk_mul_f32 v[16:17], v[0:1], v[16:17]
	v_pk_mov_b32 v[36:37], v[20:21], v[22:23] op_sel:[1,0]
	v_mov_b32_e32 v21, v23
	v_pk_add_f32 v[20:21], v[36:37], v[20:21]
	v_mov_b32_e32 v22, v18
	v_mov_b32_e32 v23, v16
	v_mov_b32_e32 v16, v19
	v_pk_add_f32 v[16:17], v[22:23], v[16:17]
	v_add_f32_e32 v18, v20, v21
	v_add_f32_e32 v17, v18, v17
	v_add_f32_e32 v16, v16, v17
	s_nop 1
	v_mov_b32_dpp v17, v16 quad_perm:[1,0,3,2] row_mask:0xf bank_mask:0xf
	v_fma_f32 v11, v40, v46, v50
	v_pk_mov_b32 v[20:21], v[40:41], v[12:13] op_sel:[1,0]
	v_pk_mov_b32 v[12:13], v[12:13], v[14:15] op_sel:[1,0]
	s_waitcnt lgkmcnt(0)
	v_add_f32_e32 v16, v16, v17
	s_nop 1
	v_mov_b32_dpp v17, v16 quad_perm:[2,3,0,1] row_mask:0xf bank_mask:0xf
	s_waitcnt lgkmcnt(0)
	v_add_f32_e32 v16, v16, v17
	s_nop 1
	v_mov_b32_dpp v17, v16 row_half_mirror row_mask:0xf bank_mask:0xf
	s_nop 1
	v_mov_b32_dpp v17, v17 quad_perm:[3,2,1,0] row_mask:0xf bank_mask:0xf
	s_waitcnt lgkmcnt(0)
	v_add_f32_e32 v16, v16, v17
	s_nop 1
	v_mov_b32_dpp v17, v16 row_mirror row_mask:0xf bank_mask:0xf
	s_nop 1
	v_mov_b32_dpp v17, v17 row_half_mirror row_mask:0xf bank_mask:0xf
	s_waitcnt lgkmcnt(0)
	v_add_f32_e32 v17, v16, v17
	v_max_f32_e32 v47, v38, v17
	v_sub_f32_e32 v16, v38, v47
	v_sub_f32_e32 v17, v17, v47
	v_exp_f32_e32 v16, v16
	v_exp_f32_e32 v18, v17
	v_pk_mul_f32 v[12:13], v[12:13], v[46:47] op_sel_hi:[1,0]
	v_pk_mul_f32 v[20:21], v[20:21], v[46:47] op_sel_hi:[1,0]
	v_fma_f32 v51, v11, v16, v18
	v_pk_fma_f32 v[12:13], v[34:35], v[50:51], v[12:13] op_sel_hi:[1,0,1]
	v_pk_fma_f32 v[20:21], v[32:33], v[50:51], v[20:21] op_sel_hi:[1,0,1]
	v_pk_mul_f32 v[12:13], v[12:13], v[16:17] op_sel_hi:[1,0]
	v_pk_mul_f32 v[20:21], v[20:21], v[16:17] op_sel_hi:[1,0]
	s_waitcnt vmcnt(0)
	v_pk_fma_f32 v[36:37], v[44:45], v[18:19], v[12:13] op_sel_hi:[1,0,1]
	v_pk_mov_b32 v[12:13], v[14:15], v[8:9] op_sel:[1,0]
	v_mov_b32_e32 v8, v9
	v_mov_b32_e32 v9, v10
	v_pk_mul_f32 v[8:9], v[8:9], v[46:47] op_sel_hi:[1,0]
	v_pk_mul_f32 v[12:13], v[12:13], v[46:47] op_sel_hi:[1,0]
	v_pk_fma_f32 v[8:9], v[30:31], v[50:51], v[8:9] op_sel_hi:[1,0,1]
	v_pk_fma_f32 v[12:13], v[28:29], v[50:51], v[12:13] op_sel_hi:[1,0,1]
	v_pk_mul_f32 v[8:9], v[8:9], v[16:17] op_sel_hi:[1,0]
	v_pk_mul_f32 v[12:13], v[12:13], v[16:17] op_sel_hi:[1,0]
	v_pk_fma_f32 v[34:35], v[26:27], v[18:19], v[8:9] op_sel_hi:[1,0,1]
	v_lshlrev_b32_e32 v8, 4, v76
	v_sub_u32_e32 v8, 0x800, v8
	v_ashrrev_i32_e32 v9, 31, v8
	v_lshlrev_b64 v[8:9], 9, v[8:9]
	v_lshl_add_u64 v[8:9], v[8:9], 0, s[6:7]
	v_or_b32_e32 v8, v8, v74
	v_lshlrev_b64 v[8:9], 2, v[8:9]
	v_pk_fma_f32 v[32:33], v[24:25], v[18:19], v[12:13] op_sel_hi:[1,0,1]
	v_lshl_add_u64 v[10:11], s[12:13], 0, v[8:9]
	v_lshl_add_u64 v[12:13], s[14:15], 0, v[8:9]
	v_pk_fma_f32 v[38:39], v[42:43], v[18:19], v[20:21] op_sel_hi:[1,0,1]
	global_load_dwordx4 v[16:19], v[10:11], off offset:16
	global_load_dwordx4 v[20:23], v[10:11], off
	s_nop 0
	global_load_dwordx4 v[8:11], v[12:13], off offset:16
	s_nop 0
	global_load_dwordx4 v[12:15], v[12:13], off
	s_waitcnt vmcnt(3)
	v_pk_mul_f32 v[18:19], v[2:3], v[18:19]
	s_waitcnt vmcnt(2)
	v_pk_mul_f32 v[22:23], v[6:7], v[22:23]
	v_pk_mul_f32 v[20:21], v[4:5], v[20:21]
	v_pk_mul_f32 v[16:17], v[0:1], v[16:17]
	v_pk_mov_b32 v[24:25], v[20:21], v[22:23] op_sel:[1,0]
	v_mov_b32_e32 v21, v23
	v_pk_add_f32 v[20:21], v[24:25], v[20:21]
	v_mov_b32_e32 v22, v18
	v_mov_b32_e32 v23, v16
	v_mov_b32_e32 v16, v19
	v_pk_add_f32 v[16:17], v[22:23], v[16:17]
	v_add_f32_e32 v18, v20, v21
	v_add_f32_e32 v17, v18, v17
	v_add_f32_e32 v16, v16, v17
	s_nop 1
	v_mov_b32_dpp v17, v16 quad_perm:[1,0,3,2] row_mask:0xf bank_mask:0xf
	s_waitcnt lgkmcnt(0)
	v_add_f32_e32 v16, v16, v17
	s_nop 1
	v_mov_b32_dpp v17, v16 quad_perm:[2,3,0,1] row_mask:0xf bank_mask:0xf
	s_waitcnt lgkmcnt(0)
	v_add_f32_e32 v16, v16, v17
	s_nop 1
	v_mov_b32_dpp v17, v16 row_half_mirror row_mask:0xf bank_mask:0xf
	s_nop 1
	v_mov_b32_dpp v17, v17 quad_perm:[3,2,1,0] row_mask:0xf bank_mask:0xf
	s_waitcnt lgkmcnt(0)
	v_add_f32_e32 v16, v16, v17
	s_nop 1
	v_mov_b32_dpp v17, v16 row_mirror row_mask:0xf bank_mask:0xf
	s_nop 1
	v_mov_b32_dpp v17, v17 row_half_mirror row_mask:0xf bank_mask:0xf
	s_waitcnt lgkmcnt(0)
	v_add_f32_e32 v16, v16, v17
	v_max_f32_e32 v43, v47, v16
	v_sub_f32_e32 v16, v16, v43
	v_exp_f32_e32 v40, v16
	v_lshlrev_b32_e32 v16, 4, v75
	v_sub_f32_e32 v17, v47, v43
	v_sub_u32_e32 v16, 0x800, v16
	v_exp_f32_e32 v42, v17
	v_ashrrev_i32_e32 v17, 31, v16
	v_lshlrev_b64 v[16:17], 9, v[16:17]
	v_lshl_add_u64 v[16:17], v[16:17], 0, s[6:7]
	v_or_b32_e32 v16, v16, v74
	v_lshlrev_b64 v[16:17], 2, v[16:17]
	v_lshl_add_u64 v[20:21], s[12:13], 0, v[16:17]
	v_lshl_add_u64 v[28:29], s[14:15], 0, v[16:17]
	global_load_dwordx4 v[16:19], v[20:21], off offset:16
	s_nop 0
	global_load_dwordx4 v[20:23], v[20:21], off
	s_nop 0
	global_load_dwordx4 v[24:27], v[28:29], off offset:16
	s_nop 0
	global_load_dwordx4 v[28:31], v[28:29], off
	v_fma_f32 v41, v51, v42, v40
	s_waitcnt vmcnt(3)
	v_pk_mul_f32 v[18:19], v[2:3], v[18:19]
	s_waitcnt vmcnt(2)
	v_pk_mul_f32 v[22:23], v[6:7], v[22:23]
	v_pk_mul_f32 v[20:21], v[4:5], v[20:21]
	v_pk_mul_f32 v[16:17], v[0:1], v[16:17]
	v_pk_mov_b32 v[44:45], v[20:21], v[22:23] op_sel:[1,0]
	v_mov_b32_e32 v21, v23
	v_pk_add_f32 v[20:21], v[44:45], v[20:21]
	v_mov_b32_e32 v22, v18
	v_mov_b32_e32 v23, v16
	v_mov_b32_e32 v16, v19
	v_pk_add_f32 v[16:17], v[22:23], v[16:17]
	v_add_f32_e32 v18, v20, v21
	v_add_f32_e32 v17, v18, v17
	v_add_f32_e32 v16, v16, v17
	s_nop 1
	v_mov_b32_dpp v17, v16 quad_perm:[1,0,3,2] row_mask:0xf bank_mask:0xf
	v_pk_mul_f32 v[22:23], v[38:39], v[42:43] op_sel_hi:[1,0]
	s_waitcnt lgkmcnt(0)
	v_add_f32_e32 v16, v16, v17
	s_nop 1
	v_mov_b32_dpp v17, v16 quad_perm:[2,3,0,1] row_mask:0xf bank_mask:0xf
	v_pk_fma_f32 v[12:13], v[12:13], v[40:41], v[22:23] op_sel_hi:[1,0,1]
	v_pk_mul_f32 v[22:23], v[36:37], v[42:43] op_sel_hi:[1,0]
	s_waitcnt lgkmcnt(0)
	v_add_f32_e32 v16, v16, v17
	s_nop 1
	v_mov_b32_dpp v17, v16 row_half_mirror row_mask:0xf bank_mask:0xf
	s_nop 1
	v_mov_b32_dpp v17, v17 quad_perm:[3,2,1,0] row_mask:0xf bank_mask:0xf
	v_pk_fma_f32 v[14:15], v[14:15], v[40:41], v[22:23] op_sel_hi:[1,0,1]
	v_pk_mul_f32 v[22:23], v[32:33], v[42:43] op_sel_hi:[1,0]
	s_waitcnt lgkmcnt(0)
	v_add_f32_e32 v16, v16, v17
	s_nop 1
	v_mov_b32_dpp v17, v16 row_mirror row_mask:0xf bank_mask:0xf
	s_nop 1
	v_mov_b32_dpp v17, v17 row_half_mirror row_mask:0xf bank_mask:0xf
	v_pk_fma_f32 v[8:9], v[8:9], v[40:41], v[22:23] op_sel_hi:[1,0,1]
	v_pk_mul_f32 v[22:23], v[34:35], v[42:43] op_sel_hi:[1,0]
	s_waitcnt lgkmcnt(0)
	v_add_f32_e32 v16, v16, v17
	v_max_f32_e32 v17, v43, v16
	v_sub_f32_e32 v18, v43, v17
	v_exp_f32_e32 v18, v18
	v_sub_f32_e32 v16, v16, v17
	v_exp_f32_e32 v20, v16
	v_pk_fma_f32 v[10:11], v[10:11], v[40:41], v[22:23] op_sel_hi:[1,0,1]
	v_pk_mul_f32 v[12:13], v[12:13], v[18:19] op_sel_hi:[1,0]
	v_pk_mul_f32 v[14:15], v[14:15], v[18:19] op_sel_hi:[1,0]
	v_pk_mul_f32 v[8:9], v[8:9], v[18:19] op_sel_hi:[1,0]
	v_pk_mul_f32 v[10:11], v[10:11], v[18:19] op_sel_hi:[1,0]
	v_fma_f32 v16, v41, v18, v20
	s_waitcnt vmcnt(0)
	v_pk_fma_f32 v[12:13], v[28:29], v[20:21], v[12:13] op_sel_hi:[1,0,1]
	v_pk_fma_f32 v[14:15], v[30:31], v[20:21], v[14:15] op_sel_hi:[1,0,1]
	v_pk_fma_f32 v[8:9], v[24:25], v[20:21], v[8:9] op_sel_hi:[1,0,1]
	v_pk_fma_f32 v[10:11], v[26:27], v[20:21], v[10:11] op_sel_hi:[1,0,1]
	s_and_saveexec_b64 s[6:7], s[38:39]
	s_cbranch_execz .LBB0_572
	global_load_dwordx4 v[18:21], v[48:49], off
	global_load_dwordx4 v[22:25], v[48:49], off offset:16
	global_load_dwordx4 v[26:29], v[48:49], off offset:2048
	global_load_dwordx4 v[30:33], v[48:49], off offset:2064
	s_waitcnt vmcnt(3)
	v_pk_mul_f32 v[6:7], v[6:7], v[20:21]
	v_pk_mul_f32 v[4:5], v[4:5], v[18:19]
	s_waitcnt vmcnt(2)
	v_pk_mul_f32 v[2:3], v[2:3], v[24:25]
	v_pk_mul_f32 v[0:1], v[0:1], v[22:23]
	v_pk_mov_b32 v[18:19], v[4:5], v[6:7] op_sel:[1,0]
	v_mov_b32_e32 v5, v7
	v_mov_b32_e32 v6, v2
	v_mov_b32_e32 v7, v0
	v_mov_b32_e32 v0, v3
	v_pk_add_f32 v[2:3], v[18:19], v[4:5]
	v_pk_add_f32 v[0:1], v[6:7], v[0:1]
	v_add_f32_e32 v2, v2, v3
	v_add_f32_e32 v1, v2, v1
	v_add_f32_e32 v0, v0, v1
	s_nop 1
	v_mov_b32_dpp v1, v0 quad_perm:[1,0,3,2] row_mask:0xf bank_mask:0xf
	v_max_f32_e32 v2, v17, v17
	s_waitcnt lgkmcnt(0)
	v_add_f32_e32 v0, v0, v1
	s_nop 1
	v_mov_b32_dpp v1, v0 quad_perm:[2,3,0,1] row_mask:0xf bank_mask:0xf
	s_waitcnt lgkmcnt(0)
	v_add_f32_e32 v0, v0, v1
	s_nop 1
	v_mov_b32_dpp v1, v0 row_half_mirror row_mask:0xf bank_mask:0xf
	s_nop 1
	v_mov_b32_dpp v1, v1 quad_perm:[3,2,1,0] row_mask:0xf bank_mask:0xf
	s_waitcnt lgkmcnt(0)
	v_add_f32_e32 v0, v0, v1
	s_nop 1
	v_mov_b32_dpp v1, v0 row_mirror row_mask:0xf bank_mask:0xf
	s_nop 1
	v_mov_b32_dpp v1, v1 row_half_mirror row_mask:0xf bank_mask:0xf
	s_waitcnt lgkmcnt(0)
	v_add_f32_e32 v0, v0, v1
	v_max_f32_e32 v3, v2, v0
	v_sub_f32_e32 v1, v17, v3
	v_sub_f32_e32 v2, v0, v3
	v_exp_f32_e32 v0, v1
	v_exp_f32_e32 v2, v2
	v_mov_b32_e32 v17, v3
	v_pk_mul_f32 v[4:5], v[12:13], v[0:1] op_sel_hi:[1,0]
	v_fma_f32 v16, v16, v0, v2
	v_pk_mul_f32 v[6:7], v[14:15], v[0:1] op_sel_hi:[1,0]
	v_pk_mul_f32 v[8:9], v[8:9], v[0:1] op_sel_hi:[1,0]
	v_pk_mul_f32 v[0:1], v[10:11], v[0:1] op_sel_hi:[1,0]
	s_waitcnt vmcnt(1)
	v_pk_fma_f32 v[12:13], v[26:27], v[2:3], v[4:5] op_sel_hi:[1,0,1]
	v_pk_fma_f32 v[14:15], v[28:29], v[2:3], v[6:7] op_sel_hi:[1,0,1]
	s_waitcnt vmcnt(0)
	v_pk_fma_f32 v[8:9], v[30:31], v[2:3], v[8:9] op_sel_hi:[1,0,1]
	v_pk_fma_f32 v[10:11], v[32:33], v[2:3], v[0:1] op_sel_hi:[1,0,1]

.LBB0_1282:
	v_mov_b32_e32 v0, v190
	v_and_b32_e32 v9, 64, v214
	s_ashr_i32 s12, s1, 2
	v_bfe_u32 v1, v0, 4, 2
	v_readlane_b32 s6, v240, 36
	v_xor_b32_e32 v8, 1, v214
	v_add_u32_e32 v59, 64, v9
	v_or_b32_e32 v128, s6, v1
	s_lshl_b32 s6, s12, 9
	v_cmp_lt_i32_e32 vcc, v8, v59
	s_ashr_i32 s7, s6, 31
	s_lshl_b64 s[6:7], s[6:7], 2
	v_cndmask_b32_e32 v8, v214, v8, vcc
	v_readlane_b32 s10, v240, 60
	v_lshlrev_b32_e32 v67, 2, v8
	v_xor_b32_e32 v8, 2, v214
	v_readlane_b32 s11, v240, 61
	s_add_u32 s9, s10, s6
	v_cmp_lt_i32_e32 vcc, v8, v59
	s_addc_u32 s11, s11, s7
	s_and_b32 s8, s0, 0x180
	v_cndmask_b32_e32 v8, v214, v8, vcc
	s_lshl_b32 s10, s8, 2
	v_lshlrev_b32_e32 v65, 2, v8
	v_xor_b32_e32 v8, 4, v214
	s_add_u32 s16, s9, s10
	v_cmp_lt_i32_e32 vcc, v8, v59
	s_addc_u32 s17, s11, 0
	s_ashr_i32 s13, s12, 31
	v_cndmask_b32_e32 v8, v214, v8, vcc
	s_lshl_b64 s[12:13], s[12:13], 8
	v_lshlrev_b32_e32 v63, 2, v8
	v_xor_b32_e32 v8, 8, v214
	s_add_u32 s38, s12, s4
	v_cmp_lt_i32_e32 vcc, v8, v59
	s_addc_u32 s39, s13, s5
	v_and_b32_e32 v57, 63, v0
	v_cndmask_b32_e32 v8, v214, v8, vcc
	v_lshlrev_b32_e32 v0, 3, v0
	v_lshlrev_b32_e32 v61, 2, v8
	v_lshl_add_u64 v[8:9], s[38:39], 0, v[128:129]
	v_and_b32_e32 v41, 0x78, v0
	v_lshlrev_b64 v[8:9], 9, v[8:9]
	v_lshlrev_b32_e32 v4, 2, v41
	v_or3_b32 v8, v8, v41, s8
	v_readlane_b32 s40, v241, 8
	global_load_dwordx4 v[0:3], v4, s[16:17] offset:16
	s_nop 0
	global_load_dwordx4 v[4:7], v4, s[16:17]
	v_lshlrev_b64 v[8:9], 2, v[8:9]
	v_readlane_b32 s52, v241, 20
	v_readlane_b32 s53, v241, 21
	v_readlane_b32 s54, v241, 22
	v_readlane_b32 s55, v241, 23
	v_lshl_add_u64 v[10:11], s[52:53], 0, v[8:9]
	v_readlane_b32 s41, v241, 9
	v_lshl_add_u64 v[12:13], s[54:55], 0, v[8:9]
	global_load_dwordx4 v[16:19], v[10:11], off offset:16
	global_load_dwordx4 v[20:23], v[10:11], off
	s_nop 0
	global_load_dwordx4 v[8:11], v[12:13], off offset:16
	s_nop 0
	global_load_dwordx4 v[12:15], v[12:13], off
	v_readlane_b32 s42, v241, 10
	v_readlane_b32 s43, v241, 11
	v_readlane_b32 s44, v241, 12
	v_readlane_b32 s45, v241, 13
	v_readlane_b32 s46, v241, 14
	v_readlane_b32 s47, v241, 15
	v_readlane_b32 s48, v241, 16
	v_readlane_b32 s49, v241, 17
	v_readlane_b32 s50, v241, 18
	v_readlane_b32 s51, v241, 19
	s_waitcnt vmcnt(3)
	v_pk_mul_f32 v[18:19], v[2:3], v[18:19]
	s_waitcnt vmcnt(2)
	v_pk_mul_f32 v[22:23], v[6:7], v[22:23]
	v_pk_mul_f32 v[20:21], v[4:5], v[20:21]
	v_pk_mul_f32 v[16:17], v[0:1], v[16:17]
	v_pk_mov_b32 v[24:25], v[20:21], v[22:23] op_sel:[1,0]
	v_mov_b32_e32 v21, v23
	v_pk_add_f32 v[20:21], v[24:25], v[20:21]
	v_mov_b32_e32 v22, v18
	v_mov_b32_e32 v23, v16
	v_mov_b32_e32 v16, v19
	v_pk_add_f32 v[16:17], v[22:23], v[16:17]
	v_add_f32_e32 v18, v20, v21
	v_add_f32_e32 v17, v18, v17
	v_add_f32_e32 v16, v16, v17
	s_nop 1
	v_mov_b32_dpp v17, v16 quad_perm:[1,0,3,2] row_mask:0xf bank_mask:0xf
	s_waitcnt lgkmcnt(0)
	v_add_f32_e32 v16, v16, v17
	s_nop 1
	v_mov_b32_dpp v17, v16 quad_perm:[2,3,0,1] row_mask:0xf bank_mask:0xf
	s_waitcnt lgkmcnt(0)
	v_add_f32_e32 v16, v16, v17
	s_nop 1
	v_mov_b32_dpp v17, v16 row_half_mirror row_mask:0xf bank_mask:0xf
	s_nop 1
	v_mov_b32_dpp v17, v17 quad_perm:[3,2,1,0] row_mask:0xf bank_mask:0xf
	s_waitcnt lgkmcnt(0)
	v_add_f32_e32 v16, v16, v17
	s_nop 1
	v_mov_b32_dpp v17, v16 row_mirror row_mask:0xf bank_mask:0xf
	s_nop 1
	v_mov_b32_dpp v17, v17 row_half_mirror row_mask:0xf bank_mask:0xf
	s_waitcnt lgkmcnt(0)
	v_add_f32_e32 v16, v16, v17
	v_max_f32_e32 v34, 0xf149f2ca, v16
	v_sub_f32_e32 v17, 0xf149f2ca, v34
	v_sub_f32_e32 v16, v16, v34
	v_exp_f32_e32 v17, v17
	v_exp_f32_e32 v40, v16
	v_add_u32_e32 v16, 32, v128
	v_mul_f32_e32 v42, 0, v17
	v_fma_f32 v35, 0, v17, v40
	v_mov_b32_e32 v17, v129
	v_lshl_add_u64 v[16:17], s[38:39], 0, v[16:17]
	v_lshlrev_b64 v[16:17], 9, v[16:17]
	v_or3_b32 v16, v16, v41, s8
	v_lshlrev_b64 v[16:17], 2, v[16:17]
	v_lshl_add_u64 v[18:19], s[52:53], 0, v[16:17]
	v_lshl_add_u64 v[20:21], s[54:55], 0, v[16:17]
	global_load_dwordx4 v[24:27], v[18:19], off offset:16
	global_load_dwordx4 v[28:31], v[18:19], off
	s_nop 0
	global_load_dwordx4 v[16:19], v[20:21], off offset:16
	s_nop 0
	global_load_dwordx4 v[20:23], v[20:21], off
	s_waitcnt vmcnt(3)
	v_pk_mul_f32 v[26:27], v[2:3], v[26:27]
	s_waitcnt vmcnt(2)
	v_pk_mul_f32 v[30:31], v[6:7], v[30:31]
	v_pk_mul_f32 v[28:29], v[4:5], v[28:29]
	v_pk_mul_f32 v[24:25], v[0:1], v[24:25]
	v_pk_mov_b32 v[32:33], v[28:29], v[30:31] op_sel:[1,0]
	v_mov_b32_e32 v29, v31
	v_pk_add_f32 v[28:29], v[32:33], v[28:29]
	v_mov_b32_e32 v30, v26
	v_mov_b32_e32 v31, v24
	v_mov_b32_e32 v24, v27
	v_pk_add_f32 v[24:25], v[30:31], v[24:25]
	v_add_f32_e32 v26, v28, v29
	v_add_f32_e32 v25, v26, v25
	v_add_f32_e32 v24, v24, v25
	s_nop 1
	v_mov_b32_dpp v25, v24 quad_perm:[1,0,3,2] row_mask:0xf bank_mask:0xf
	s_waitcnt lgkmcnt(0)
	v_add_f32_e32 v24, v24, v25
	s_nop 1
	v_mov_b32_dpp v25, v24 quad_perm:[2,3,0,1] row_mask:0xf bank_mask:0xf
	s_waitcnt lgkmcnt(0)
	v_add_f32_e32 v24, v24, v25
	s_nop 1
	v_mov_b32_dpp v25, v24 row_half_mirror row_mask:0xf bank_mask:0xf
	s_nop 1
	v_mov_b32_dpp v25, v25 quad_perm:[3,2,1,0] row_mask:0xf bank_mask:0xf
	s_waitcnt lgkmcnt(0)
	v_add_f32_e32 v24, v24, v25
	s_nop 1
	v_mov_b32_dpp v25, v24 row_mirror row_mask:0xf bank_mask:0xf
	s_nop 1
	v_mov_b32_dpp v25, v25 row_half_mirror row_mask:0xf bank_mask:0xf
	s_waitcnt lgkmcnt(0)
	v_add_f32_e32 v24, v24, v25
	v_max_f32_e32 v45, v34, v24
	v_sub_f32_e32 v25, v34, v45
	v_sub_f32_e32 v24, v24, v45
	v_exp_f32_e32 v44, v25
	v_exp_f32_e32 v46, v24
	v_add_u32_e32 v24, 64, v128
	v_mov_b32_e32 v25, v129
	v_lshl_add_u64 v[24:25], s[38:39], 0, v[24:25]
	v_lshlrev_b64 v[24:25], 9, v[24:25]
	v_or3_b32 v24, v24, v41, s8
	v_lshlrev_b64 v[24:25], 2, v[24:25]
	v_lshl_add_u64 v[26:27], s[52:53], 0, v[24:25]
	v_lshl_add_u64 v[28:29], s[54:55], 0, v[24:25]
	v_fma_f32 v47, v35, v44, v46
	global_load_dwordx4 v[32:35], v[26:27], off offset:16
	global_load_dwordx4 v[36:39], v[26:27], off
	s_nop 0
	global_load_dwordx4 v[24:27], v[28:29], off offset:16
	s_nop 0
	global_load_dwordx4 v[28:31], v[28:29], off
	s_waitcnt vmcnt(3)
	v_pk_mul_f32 v[34:35], v[2:3], v[34:35]
	s_waitcnt vmcnt(2)
	v_pk_mul_f32 v[38:39], v[6:7], v[38:39]
	v_pk_mul_f32 v[36:37], v[4:5], v[36:37]
	v_pk_mul_f32 v[32:33], v[0:1], v[32:33]
	v_pk_mov_b32 v[48:49], v[36:37], v[38:39] op_sel:[1,0]
	v_mov_b32_e32 v37, v39
	v_pk_add_f32 v[36:37], v[48:49], v[36:37]
	v_mov_b32_e32 v38, v34
	v_mov_b32_e32 v39, v32
	v_mov_b32_e32 v32, v35
	v_pk_add_f32 v[32:33], v[38:39], v[32:33]
	v_add_f32_e32 v34, v36, v37
	v_add_f32_e32 v33, v34, v33
	v_add_f32_e32 v32, v32, v33
	s_nop 1
	v_mov_b32_dpp v33, v32 quad_perm:[1,0,3,2] row_mask:0xf bank_mask:0xf
	s_waitcnt lgkmcnt(0)
	v_add_f32_e32 v32, v32, v33
	s_nop 1
	v_mov_b32_dpp v33, v32 quad_perm:[2,3,0,1] row_mask:0xf bank_mask:0xf
	s_waitcnt lgkmcnt(0)
	v_add_f32_e32 v32, v32, v33
	s_nop 1
	v_mov_b32_dpp v33, v32 row_half_mirror row_mask:0xf bank_mask:0xf
	s_nop 1
	v_mov_b32_dpp v33, v33 quad_perm:[3,2,1,0] row_mask:0xf bank_mask:0xf
	s_waitcnt lgkmcnt(0)
	v_add_f32_e32 v32, v32, v33
	s_nop 1
	v_mov_b32_dpp v33, v32 row_mirror row_mask:0xf bank_mask:0xf
	s_nop 1
	v_mov_b32_dpp v33, v33 row_half_mirror row_mask:0xf bank_mask:0xf
	s_waitcnt lgkmcnt(0)
	v_add_f32_e32 v32, v32, v33
	v_max_f32_e32 v43, v45, v32
	v_sub_f32_e32 v33, v45, v43
	v_sub_f32_e32 v32, v32, v43
	v_exp_f32_e32 v48, v33
	v_exp_f32_e32 v56, v32
	v_add_u32_e32 v32, 0x60, v128
	v_mov_b32_e32 v33, v129
	v_lshl_add_u64 v[32:33], s[38:39], 0, v[32:33]
	v_lshlrev_b64 v[32:33], 9, v[32:33]
	v_or3_b32 v32, v32, v41, s8
	v_lshlrev_b64 v[32:33], 2, v[32:33]
	v_lshl_add_u64 v[36:37], s[52:53], 0, v[32:33]
	v_lshl_add_u64 v[50:51], s[54:55], 0, v[32:33]
	global_load_dwordx4 v[32:35], v[36:37], off offset:16
	s_nop 0
	global_load_dwordx4 v[36:39], v[36:37], off
	s_nop 0
	global_load_dwordx4 v[68:71], v[50:51], off offset:16
	s_nop 0
	global_load_dwordx4 v[50:53], v[50:51], off
	v_fma_f32 v45, v47, v48, v56
	v_pk_fma_f32 v[12:13], v[12:13], v[40:41], v[42:43] op_sel_hi:[1,0,0]
	v_pk_fma_f32 v[8:9], v[8:9], v[40:41], v[42:43] op_sel_hi:[1,0,0]
	v_pk_mul_f32 v[12:13], v[12:13], v[44:45] op_sel_hi:[1,0]
	v_pk_mul_f32 v[8:9], v[8:9], v[44:45] op_sel_hi:[1,0]
	v_pk_fma_f32 v[12:13], v[20:21], v[46:47], v[12:13] op_sel_hi:[1,0,1]
	v_pk_fma_f32 v[8:9], v[16:17], v[46:47], v[8:9] op_sel_hi:[1,0,1]
	v_pk_mul_f32 v[12:13], v[12:13], v[48:49] op_sel_hi:[1,0]
	v_pk_mul_f32 v[8:9], v[8:9], v[48:49] op_sel_hi:[1,0]
	s_waitcnt vmcnt(4)
	v_pk_fma_f32 v[12:13], v[28:29], v[56:57], v[12:13] op_sel_hi:[1,0,1]
	v_pk_fma_f32 v[8:9], v[24:25], v[56:57], v[8:9] op_sel_hi:[1,0,1]
	s_waitcnt vmcnt(3)
	v_pk_mul_f32 v[34:35], v[2:3], v[34:35]
	s_waitcnt vmcnt(2)
	v_pk_mul_f32 v[38:39], v[6:7], v[38:39]
	v_pk_mul_f32 v[36:37], v[4:5], v[36:37]
	v_pk_mul_f32 v[32:33], v[0:1], v[32:33]
	v_pk_mov_b32 v[54:55], v[36:37], v[38:39] op_sel:[1,0]
	v_mov_b32_e32 v37, v39
	v_pk_add_f32 v[36:37], v[54:55], v[36:37]
	v_mov_b32_e32 v38, v34
	v_mov_b32_e32 v39, v32
	v_mov_b32_e32 v32, v35
	v_pk_add_f32 v[32:33], v[38:39], v[32:33]
	v_add_f32_e32 v34, v36, v37
	v_add_f32_e32 v33, v34, v33
	v_add_f32_e32 v32, v32, v33
	s_nop 1
	v_mov_b32_dpp v33, v32 quad_perm:[1,0,3,2] row_mask:0xf bank_mask:0xf
	s_waitcnt lgkmcnt(0)
	v_add_f32_e32 v32, v32, v33
	s_nop 1
	v_mov_b32_dpp v33, v32 quad_perm:[2,3,0,1] row_mask:0xf bank_mask:0xf
	s_waitcnt lgkmcnt(0)
	v_add_f32_e32 v32, v32, v33
	s_nop 1
	v_mov_b32_dpp v33, v32 row_half_mirror row_mask:0xf bank_mask:0xf
	s_nop 1
	v_mov_b32_dpp v33, v33 quad_perm:[3,2,1,0] row_mask:0xf bank_mask:0xf
	s_waitcnt lgkmcnt(0)
	v_add_f32_e32 v32, v32, v33
	s_nop 1
	v_mov_b32_dpp v33, v32 row_mirror row_mask:0xf bank_mask:0xf
	s_nop 1
	v_mov_b32_dpp v33, v33 row_half_mirror row_mask:0xf bank_mask:0xf
	s_waitcnt lgkmcnt(0)
	v_add_f32_e32 v33, v32, v33
	v_max_f32_e32 v35, v43, v33
	v_sub_f32_e32 v32, v43, v35
	v_sub_f32_e32 v33, v33, v35
	v_exp_f32_e32 v32, v32
	v_exp_f32_e32 v34, v33
	s_nop 0
	v_fma_f32 v33, v45, v32, v34
	v_pk_mul_f32 v[12:13], v[12:13], v[32:33] op_sel_hi:[1,0]
	v_pk_mul_f32 v[8:9], v[8:9], v[32:33] op_sel_hi:[1,0]
	s_waitcnt vmcnt(0)
	v_pk_fma_f32 v[54:55], v[50:51], v[34:35], v[12:13] op_sel_hi:[1,0,1]
	v_pk_fma_f32 v[50:51], v[68:69], v[34:35], v[8:9] op_sel_hi:[1,0,1]
	v_pk_fma_f32 v[8:9], v[10:11], v[40:41], v[42:43] op_sel_hi:[1,0,0]
	v_pk_fma_f32 v[12:13], v[14:15], v[40:41], v[42:43] op_sel_hi:[1,0,0]
	v_pk_mul_f32 v[8:9], v[8:9], v[44:45] op_sel_hi:[1,0]
	v_pk_mul_f32 v[12:13], v[12:13], v[44:45] op_sel_hi:[1,0]
	v_pk_fma_f32 v[8:9], v[18:19], v[46:47], v[8:9] op_sel_hi:[1,0,1]
	v_pk_fma_f32 v[12:13], v[22:23], v[46:47], v[12:13] op_sel_hi:[1,0,1]
	v_pk_mul_f32 v[8:9], v[8:9], v[48:49] op_sel_hi:[1,0]
	v_pk_mul_f32 v[12:13], v[12:13], v[48:49] op_sel_hi:[1,0]
	v_pk_fma_f32 v[8:9], v[26:27], v[56:57], v[8:9] op_sel_hi:[1,0,1]
	v_pk_fma_f32 v[12:13], v[30:31], v[56:57], v[12:13] op_sel_hi:[1,0,1]
	v_pk_mul_f32 v[8:9], v[8:9], v[32:33] op_sel_hi:[1,0]
	v_pk_mul_f32 v[12:13], v[12:13], v[32:33] op_sel_hi:[1,0]
	v_pk_fma_f32 v[48:49], v[70:71], v[34:35], v[8:9] op_sel_hi:[1,0,1]
	v_add_u32_e32 v8, 0x80, v128
	v_mov_b32_e32 v9, v129
	v_lshl_add_u64 v[8:9], s[38:39], 0, v[8:9]
	v_lshlrev_b64 v[8:9], 9, v[8:9]
	v_or3_b32 v8, v8, v41, s8
	v_lshlrev_b64 v[8:9], 2, v[8:9]
	v_pk_fma_f32 v[52:53], v[52:53], v[34:35], v[12:13] op_sel_hi:[1,0,1]
	v_lshl_add_u64 v[10:11], s[52:53], 0, v[8:9]
	v_lshl_add_u64 v[12:13], s[54:55], 0, v[8:9]
	global_load_dwordx4 v[16:19], v[10:11], off offset:16
	global_load_dwordx4 v[20:23], v[10:11], off
	s_nop 0
	global_load_dwordx4 v[8:11], v[12:13], off offset:16
	s_nop 0
	global_load_dwordx4 v[12:15], v[12:13], off
	s_waitcnt vmcnt(3)
	v_pk_mul_f32 v[18:19], v[2:3], v[18:19]
	s_waitcnt vmcnt(2)
	v_pk_mul_f32 v[22:23], v[6:7], v[22:23]
	v_pk_mul_f32 v[20:21], v[4:5], v[20:21]
	v_pk_mul_f32 v[16:17], v[0:1], v[16:17]
	v_pk_mov_b32 v[24:25], v[20:21], v[22:23] op_sel:[1,0]
	v_mov_b32_e32 v21, v23
	v_pk_add_f32 v[20:21], v[24:25], v[20:21]
	v_mov_b32_e32 v22, v18
	v_mov_b32_e32 v23, v16
	v_mov_b32_e32 v16, v19
	v_pk_add_f32 v[16:17], v[22:23], v[16:17]
	v_add_f32_e32 v18, v20, v21
	v_add_f32_e32 v17, v18, v17
	v_add_f32_e32 v16, v16, v17
	s_nop 1
	v_mov_b32_dpp v17, v16 quad_perm:[1,0,3,2] row_mask:0xf bank_mask:0xf
	s_waitcnt lgkmcnt(0)
	v_add_f32_e32 v16, v16, v17
	s_nop 1
	v_mov_b32_dpp v17, v16 quad_perm:[2,3,0,1] row_mask:0xf bank_mask:0xf
	s_waitcnt lgkmcnt(0)
	v_add_f32_e32 v16, v16, v17
	s_nop 1
	v_mov_b32_dpp v17, v16 row_half_mirror row_mask:0xf bank_mask:0xf
	s_nop 1
	v_mov_b32_dpp v17, v17 quad_perm:[3,2,1,0] row_mask:0xf bank_mask:0xf
	s_waitcnt lgkmcnt(0)
	v_add_f32_e32 v16, v16, v17
	s_nop 1
	v_mov_b32_dpp v17, v16 row_mirror row_mask:0xf bank_mask:0xf
	s_nop 1
	v_mov_b32_dpp v17, v17 row_half_mirror row_mask:0xf bank_mask:0xf
	s_waitcnt lgkmcnt(0)
	v_add_f32_e32 v16, v16, v17
	v_max_f32_e32 v34, v35, v16
	v_sub_f32_e32 v17, v35, v34
	v_sub_f32_e32 v16, v16, v34
	v_exp_f32_e32 v58, v17
	v_exp_f32_e32 v56, v16
	v_add_u32_e32 v16, 0xa0, v128
	v_mov_b32_e32 v17, v129
	v_lshl_add_u64 v[16:17], s[38:39], 0, v[16:17]
	v_lshlrev_b64 v[16:17], 9, v[16:17]
	v_or3_b32 v16, v16, v41, s8
	v_lshlrev_b64 v[16:17], 2, v[16:17]
	v_lshl_add_u64 v[18:19], s[52:53], 0, v[16:17]
	v_lshl_add_u64 v[20:21], s[54:55], 0, v[16:17]
	global_load_dwordx4 v[24:27], v[18:19], off offset:16
	global_load_dwordx4 v[28:31], v[18:19], off
	s_nop 0
	global_load_dwordx4 v[16:19], v[20:21], off offset:16
	s_nop 0
	global_load_dwordx4 v[20:23], v[20:21], off
	v_fma_f32 v35, v33, v58, v56
	s_waitcnt vmcnt(3)
	v_pk_mul_f32 v[26:27], v[2:3], v[26:27]
	s_waitcnt vmcnt(2)
	v_pk_mul_f32 v[30:31], v[6:7], v[30:31]
	v_pk_mul_f32 v[28:29], v[4:5], v[28:29]
	v_pk_mul_f32 v[24:25], v[0:1], v[24:25]
	v_pk_mov_b32 v[32:33], v[28:29], v[30:31] op_sel:[1,0]
	v_mov_b32_e32 v29, v31
	v_pk_add_f32 v[28:29], v[32:33], v[28:29]
	v_mov_b32_e32 v30, v26
	v_mov_b32_e32 v31, v24
	v_mov_b32_e32 v24, v27
	v_pk_add_f32 v[24:25], v[30:31], v[24:25]
	v_add_f32_e32 v26, v28, v29
	v_add_f32_e32 v25, v26, v25
	v_add_f32_e32 v24, v24, v25
	s_nop 1
	v_mov_b32_dpp v25, v24 quad_perm:[1,0,3,2] row_mask:0xf bank_mask:0xf
	s_waitcnt lgkmcnt(0)
	v_add_f32_e32 v24, v24, v25
	s_nop 1
	v_mov_b32_dpp v25, v24 quad_perm:[2,3,0,1] row_mask:0xf bank_mask:0xf
	s_waitcnt lgkmcnt(0)
	v_add_f32_e32 v24, v24, v25
	s_nop 1
	v_mov_b32_dpp v25, v24 row_half_mirror row_mask:0xf bank_mask:0xf
	s_nop 1
	v_mov_b32_dpp v25, v25 quad_perm:[3,2,1,0] row_mask:0xf bank_mask:0xf
	s_waitcnt lgkmcnt(0)
	v_add_f32_e32 v24, v24, v25
	s_nop 1
	v_mov_b32_dpp v25, v24 row_mirror row_mask:0xf bank_mask:0xf
	s_nop 1
	v_mov_b32_dpp v25, v25 row_half_mirror row_mask:0xf bank_mask:0xf
	s_waitcnt lgkmcnt(0)
	v_add_f32_e32 v24, v24, v25
	v_max_f32_e32 v40, v34, v24
	v_sub_f32_e32 v25, v34, v40
	v_sub_f32_e32 v24, v24, v40
	v_exp_f32_e32 v62, v25
	v_exp_f32_e32 v60, v24
	v_add_u32_e32 v24, 0xc0, v128
	v_mov_b32_e32 v25, v129
	v_lshl_add_u64 v[24:25], s[38:39], 0, v[24:25]
	v_lshlrev_b64 v[24:25], 9, v[24:25]
	v_or3_b32 v24, v24, v41, s8
	v_lshlrev_b64 v[24:25], 2, v[24:25]
	v_lshl_add_u64 v[26:27], s[52:53], 0, v[24:25]
	v_lshl_add_u64 v[28:29], s[54:55], 0, v[24:25]
	v_fma_f32 v44, v35, v62, v60
	global_load_dwordx4 v[32:35], v[26:27], off offset:16
	global_load_dwordx4 v[36:39], v[26:27], off
	s_nop 0
	global_load_dwordx4 v[24:27], v[28:29], off offset:16
	s_nop 0
	global_load_dwordx4 v[28:31], v[28:29], off
	v_add_u32_e32 v128, 0xe0, v128
	s_waitcnt vmcnt(3)
	v_pk_mul_f32 v[34:35], v[2:3], v[34:35]
	s_waitcnt vmcnt(2)
	v_pk_mul_f32 v[38:39], v[6:7], v[38:39]
	v_pk_mul_f32 v[36:37], v[4:5], v[36:37]
	v_pk_mul_f32 v[32:33], v[0:1], v[32:33]
	v_pk_mov_b32 v[42:43], v[36:37], v[38:39] op_sel:[1,0]
	v_mov_b32_e32 v37, v39
	v_pk_add_f32 v[36:37], v[42:43], v[36:37]
	v_mov_b32_e32 v38, v34
	v_mov_b32_e32 v39, v32
	v_mov_b32_e32 v32, v35
	v_pk_add_f32 v[32:33], v[38:39], v[32:33]
	v_add_f32_e32 v34, v36, v37
	v_add_f32_e32 v33, v34, v33
	v_add_f32_e32 v32, v32, v33
	s_nop 1
	v_mov_b32_dpp v33, v32 quad_perm:[1,0,3,2] row_mask:0xf bank_mask:0xf
	s_waitcnt lgkmcnt(0)
	v_add_f32_e32 v32, v32, v33
	s_nop 1
	v_mov_b32_dpp v33, v32 quad_perm:[2,3,0,1] row_mask:0xf bank_mask:0xf
	s_waitcnt lgkmcnt(0)
	v_add_f32_e32 v32, v32, v33
	s_nop 1
	v_mov_b32_dpp v33, v32 row_half_mirror row_mask:0xf bank_mask:0xf
	s_nop 1
	v_mov_b32_dpp v33, v33 quad_perm:[3,2,1,0] row_mask:0xf bank_mask:0xf
	s_waitcnt lgkmcnt(0)
	v_add_f32_e32 v32, v32, v33
	s_nop 1
	v_mov_b32_dpp v33, v32 row_mirror row_mask:0xf bank_mask:0xf
	s_nop 1
	v_mov_b32_dpp v33, v33 row_half_mirror row_mask:0xf bank_mask:0xf
	s_waitcnt lgkmcnt(0)
	v_add_f32_e32 v32, v32, v33
	v_max_f32_e32 v68, v40, v32
	v_sub_f32_e32 v33, v40, v68
	v_sub_f32_e32 v32, v32, v68
	v_exp_f32_e32 v66, v33
	v_exp_f32_e32 v64, v32
	v_lshl_add_u64 v[32:33], s[38:39], 0, v[128:129]
	v_lshlrev_b64 v[32:33], 9, v[32:33]
	v_or3_b32 v32, v32, v41, s8
	v_lshlrev_b64 v[32:33], 2, v[32:33]
	v_fma_f32 v69, v44, v66, v64
	v_lshl_add_u64 v[34:35], s[52:53], 0, v[32:33]
	v_lshl_add_u64 v[44:45], s[54:55], 0, v[32:33]
	global_load_dwordx4 v[36:39], v[34:35], off offset:16
	global_load_dwordx4 v[40:43], v[34:35], off
	s_nop 0
	global_load_dwordx4 v[32:35], v[44:45], off offset:16
	s_nop 0
	global_load_dwordx4 v[44:47], v[44:45], off
	s_waitcnt vmcnt(3)
	v_pk_mul_f32 v[2:3], v[2:3], v[38:39]
	s_waitcnt vmcnt(2)
	v_pk_mul_f32 v[6:7], v[6:7], v[42:43]
	v_pk_mul_f32 v[4:5], v[4:5], v[40:41]
	v_pk_mul_f32 v[0:1], v[0:1], v[36:37]
	v_pk_mov_b32 v[40:41], v[4:5], v[6:7] op_sel:[1,0]
	v_mov_b32_e32 v5, v7
	v_pk_add_f32 v[4:5], v[40:41], v[4:5]
	v_mov_b32_e32 v6, v2
	v_mov_b32_e32 v7, v0
	v_mov_b32_e32 v0, v3
	v_pk_add_f32 v[0:1], v[6:7], v[0:1]
	v_add_f32_e32 v2, v4, v5
	v_add_f32_e32 v1, v2, v1
	v_add_f32_e32 v0, v0, v1
	s_nop 1
	v_mov_b32_dpp v1, v0 quad_perm:[1,0,3,2] row_mask:0xf bank_mask:0xf
	v_xor_b32_e32 v3, 32, v214
	v_pk_mul_f32 v[6:7], v[52:53], v[58:59] op_sel_hi:[1,0]
	s_waitcnt lgkmcnt(0)
	v_add_f32_e32 v0, v0, v1
	s_nop 1
	v_mov_b32_dpp v1, v0 quad_perm:[2,3,0,1] row_mask:0xf bank_mask:0xf
	v_pk_fma_f32 v[6:7], v[14:15], v[56:57], v[6:7] op_sel_hi:[1,0,1]
	v_pk_mul_f32 v[14:15], v[50:51], v[58:59] op_sel_hi:[1,0]
	v_pk_mul_f32 v[6:7], v[6:7], v[62:63] op_sel_hi:[1,0]
	v_pk_fma_f32 v[8:9], v[8:9], v[56:57], v[14:15] op_sel_hi:[1,0,1]
	s_waitcnt lgkmcnt(0)
	v_add_f32_e32 v0, v0, v1
	s_nop 1
	v_mov_b32_dpp v1, v0 row_half_mirror row_mask:0xf bank_mask:0xf
	s_nop 1
	v_mov_b32_dpp v1, v1 quad_perm:[3,2,1,0] row_mask:0xf bank_mask:0xf
	v_pk_mul_f32 v[8:9], v[8:9], v[62:63] op_sel_hi:[1,0]
	v_pk_fma_f32 v[6:7], v[22:23], v[60:61], v[6:7] op_sel_hi:[1,0,1]
	v_pk_fma_f32 v[8:9], v[16:17], v[60:61], v[8:9] op_sel_hi:[1,0,1]
	v_pk_mul_f32 v[16:17], v[48:49], v[58:59] op_sel_hi:[1,0]
	s_waitcnt lgkmcnt(0)
	v_add_f32_e32 v0, v0, v1
	s_nop 1
	v_mov_b32_dpp v1, v0 row_mirror row_mask:0xf bank_mask:0xf
	s_nop 1
	v_mov_b32_dpp v1, v1 row_half_mirror row_mask:0xf bank_mask:0xf
	v_pk_fma_f32 v[10:11], v[10:11], v[56:57], v[16:17] op_sel_hi:[1,0,1]
	v_pk_mul_f32 v[6:7], v[6:7], v[66:67] op_sel_hi:[1,0]
	v_pk_mul_f32 v[10:11], v[10:11], v[62:63] op_sel_hi:[1,0]
	v_pk_mul_f32 v[8:9], v[8:9], v[66:67] op_sel_hi:[1,0]
	s_waitcnt lgkmcnt(0)
	v_add_f32_e32 v0, v0, v1
	v_max_f32_e32 v1, v68, v0
	v_sub_f32_e32 v0, v0, v1
	v_exp_f32_e32 v38, v0
	v_xor_b32_e32 v0, 16, v214
	v_cmp_lt_i32_e32 vcc, v0, v59
	v_sub_f32_e32 v2, v68, v1
	v_exp_f32_e32 v36, v2
	v_cndmask_b32_e32 v0, v214, v0, vcc
	v_lshlrev_b32_e32 v37, 2, v0
	ds_bpermute_b32 v0, v37, v1
	v_cmp_lt_i32_e32 vcc, v3, v59
	v_fma_f32 v2, v69, v36, v38
	v_pk_fma_f32 v[10:11], v[18:19], v[60:61], v[10:11] op_sel_hi:[1,0,1]
	v_cndmask_b32_e32 v3, v214, v3, vcc
	s_waitcnt lgkmcnt(0)
	v_max_f32_e32 v0, v0, v0
	v_max_f32_e32 v0, v1, v0
	v_lshlrev_b32_e32 v39, 2, v3
	ds_bpermute_b32 v3, v39, v0
	v_pk_mul_f32 v[10:11], v[10:11], v[66:67] op_sel_hi:[1,0]
	v_pk_fma_f32 v[6:7], v[30:31], v[64:65], v[6:7] op_sel_hi:[1,0,1]
	v_pk_fma_f32 v[8:9], v[24:25], v[64:65], v[8:9] op_sel_hi:[1,0,1]
	v_pk_fma_f32 v[10:11], v[26:27], v[64:65], v[10:11] op_sel_hi:[1,0,1]
	s_waitcnt lgkmcnt(0)
	v_max_f32_e32 v3, v3, v3
	v_max_f32_e32 v0, v0, v3
	v_sub_f32_e32 v1, v1, v0
	v_exp_f32_e32 v40, v1
	v_pk_mul_f32 v[6:7], v[6:7], v[36:37] op_sel_hi:[1,0]
	v_pk_mul_f32 v[8:9], v[8:9], v[36:37] op_sel_hi:[1,0]
	v_pk_mul_f32 v[10:11], v[10:11], v[36:37] op_sel_hi:[1,0]
	v_mul_f32_e32 v1, v2, v40
	ds_bpermute_b32 v1, v37, v1
	s_waitcnt vmcnt(0)
	v_pk_fma_f32 v[6:7], v[46:47], v[38:39], v[6:7] op_sel_hi:[1,0,1]
	v_pk_fma_f32 v[8:9], v[32:33], v[38:39], v[8:9] op_sel_hi:[1,0,1]
	v_pk_fma_f32 v[10:11], v[34:35], v[38:39], v[10:11] op_sel_hi:[1,0,1]
	v_pk_mul_f32 v[14:15], v[8:9], v[40:41] op_sel_hi:[1,0]
	s_waitcnt lgkmcnt(0)
	v_fmac_f32_e32 v1, v2, v40
	v_pk_mul_f32 v[2:3], v[54:55], v[58:59] op_sel_hi:[1,0]
	v_pk_mul_f32 v[16:17], v[10:11], v[40:41] op_sel_hi:[1,0]
	v_pk_fma_f32 v[2:3], v[12:13], v[56:57], v[2:3] op_sel_hi:[1,0,1]
	v_pk_mul_f32 v[12:13], v[6:7], v[40:41] op_sel_hi:[1,0]
	v_pk_mul_f32 v[2:3], v[2:3], v[62:63] op_sel_hi:[1,0]
	ds_bpermute_b32 v12, v37, v12
	v_pk_fma_f32 v[2:3], v[20:21], v[60:61], v[2:3] op_sel_hi:[1,0,1]
	ds_bpermute_b32 v13, v37, v13
	v_pk_mul_f32 v[2:3], v[2:3], v[66:67] op_sel_hi:[1,0]
	ds_bpermute_b32 v14, v37, v14
	v_pk_fma_f32 v[2:3], v[28:29], v[64:65], v[2:3] op_sel_hi:[1,0,1]
	ds_bpermute_b32 v15, v37, v15
	v_pk_mul_f32 v[2:3], v[2:3], v[36:37] op_sel_hi:[1,0]
	ds_bpermute_b32 v16, v37, v16
	v_pk_fma_f32 v[2:3], v[44:45], v[38:39], v[2:3] op_sel_hi:[1,0,1]
	ds_bpermute_b32 v17, v37, v17
	v_pk_mul_f32 v[4:5], v[2:3], v[40:41] op_sel_hi:[1,0]
	ds_bpermute_b32 v4, v37, v4
	ds_bpermute_b32 v5, v37, v5
	s_waitcnt lgkmcnt(6)
	v_pk_fma_f32 v[6:7], v[6:7], v[40:41], v[12:13] op_sel_hi:[1,0,1]
	s_waitcnt lgkmcnt(4)
	v_pk_fma_f32 v[8:9], v[8:9], v[40:41], v[14:15] op_sel_hi:[1,0,1]
	s_waitcnt lgkmcnt(2)
	v_pk_fma_f32 v[10:11], v[10:11], v[40:41], v[16:17] op_sel_hi:[1,0,1]
	ds_bpermute_b32 v12, v39, v6
	s_waitcnt lgkmcnt(1)
	v_pk_fma_f32 v[2:3], v[2:3], v[40:41], v[4:5] op_sel_hi:[1,0,1]
	ds_bpermute_b32 v4, v39, v2
	ds_bpermute_b32 v5, v39, v3
	ds_bpermute_b32 v13, v39, v7
	ds_bpermute_b32 v14, v39, v8
	ds_bpermute_b32 v15, v39, v9
	ds_bpermute_b32 v16, v39, v10
	ds_bpermute_b32 v17, v39, v11
	ds_bpermute_b32 v18, v39, v1
	v_cmp_gt_u32_e32 vcc, 16, v57
	s_and_saveexec_b64 s[8:9], vcc
	s_cbranch_execz .LBB0_1284
	v_readlane_b32 s11, v240, 39
	s_waitcnt lgkmcnt(6)
	v_pk_add_f32 v[2:3], v[2:3], v[4:5]
	s_waitcnt lgkmcnt(5)
	v_pk_add_f32 v[4:5], v[6:7], v[12:13]
	v_lshl_add_u32 v19, v57, 5, s11
	ds_write_b128 v19, v[2:5] offset:20480
	s_waitcnt lgkmcnt(4)
	v_pk_add_f32 v[2:3], v[8:9], v[14:15]
	s_waitcnt lgkmcnt(2)
	v_pk_add_f32 v[4:5], v[10:11], v[16:17]
	ds_write_b128 v19, v[2:5] offset:20496
